# forget-gate tile: dead |log2|<inf select of __logf removed as well (bit-exact)
# baseline (speedup 1.0000x reference)
.LBB0_288:
	s_andn2_b64 vcc, exec, s[34:35]
	s_cbranch_vccnz .LBB0_290
	v_mul_f32_e32 v128, 0xbfb8aa3b, v182
	v_exp_f32_e32 v128, v128
	v_mul_f32_e32 v161, 0x3fb8aa3b, v203
	v_exp_f32_e32 v161, v161
	v_add_f32_e32 v128, 1.0, v128
	v_rcp_f32_e32 v157, v128
	v_mul_f32_e32 v128, 0x3fb8aa3b, v182
	v_exp_f32_e32 v128, v128
	v_add_f32_e32 v161, 1.0, v161
	v_rcp_f32_e32 v211, v161
	v_mul_f32_e32 v161, 0x3fb8aa3b, v181
	v_add_f32_e32 v128, 1.0, v128
	v_rcp_f32_e32 v206, v128
	v_mul_f32_e32 v128, 0xbfb8aa3b, v183
	v_exp_f32_e32 v128, v128
	v_exp_f32_e32 v161, v161
	v_add_f32_e32 v128, 1.0, v128
	v_rcp_f32_e32 v159, v128
	v_mul_f32_e32 v128, 0x3fb8aa3b, v183
	v_exp_f32_e32 v128, v128
	v_add_f32_e32 v161, 1.0, v161
	v_rcp_f32_e32 v215, v161
	v_add_f32_e32 v128, 1.0, v128
	v_rcp_f32_e32 v207, v128
	global_load_dwordx4 v[128:131], v[148:149], off offset:16
	global_load_dwordx4 v[132:135], v[148:149], off
	s_waitcnt vmcnt(1)
	v_pk_add_f32 v[222:223], v[128:129], 1.0 op_sel_hi:[1,0] neg_lo:[1,0] neg_hi:[1,0]
	s_waitcnt vmcnt(0)
	v_pk_add_f32 v[208:209], v[132:133], 1.0 op_sel_hi:[1,0] neg_lo:[1,0] neg_hi:[1,0]
	v_pk_add_f32 v[212:213], v[134:135], 1.0 op_sel_hi:[1,0] neg_lo:[1,0] neg_hi:[1,0]
	v_fma_f32 v132, v157, v208, v132
	v_max_f32_e32 v132, 0xda24260, v132
	v_fma_f32 v133, v159, v209, v133
	v_max_f32_e32 v133, 0xda24260, v133
	v_log_f32_e32 v132, v132
	v_mul_f32_e32 v159, 0x3fb8aa3b, v202
	v_exp_f32_e32 v159, v159
	v_pk_add_f32 v[230:231], v[130:131], 1.0 op_sel_hi:[1,0] neg_lo:[1,0] neg_hi:[1,0]
	v_mul_f32_e32 v157, 0x3f317217, v132
	v_fma_f32 v157, v132, s95, -v157
	v_fmac_f32_e32 v157, 0x3377d1cf, v132
	v_fmac_f32_e32 v157, 0x3f317217, v132
	v_add_f32_e32 v159, 1.0, v159
	v_rcp_f32_e32 v210, v159
	v_mov_b32_e32 v132, v157
	v_mul_f32_e32 v159, 0xbfb8aa3b, v203
	v_log_f32_e32 v133, v133
	v_exp_f32_e32 v159, v159
	v_pk_mul_f32 v[208:209], v[206:207], v[208:209]
	v_pk_mul_f32 v[206:207], v[210:211], v[212:213]
	v_mul_f32_e32 v157, 0x3f317217, v133
	v_fma_f32 v157, v133, s95, -v157
	v_fmac_f32_e32 v157, 0x3377d1cf, v133
	v_fmac_f32_e32 v157, 0x3f317217, v133
	v_add_f32_e32 v159, 1.0, v159
	v_rcp_f32_e32 v159, v159
	v_mov_b32_e32 v133, v157
	v_mul_f32_e32 v157, 0xbfb8aa3b, v202
	v_exp_f32_e32 v157, v157
	v_fmac_f32_e32 v135, v159, v213
	v_max_f32_e32 v135, 0xda24260, v135
	v_mul_f32_e32 v159, 0x3fb8aa3b, v180
	v_add_f32_e32 v157, 1.0, v157
	v_rcp_f32_e32 v157, v157
	v_exp_f32_e32 v159, v159
	v_lshl_add_u64 v[210:211], v[146:147], 0, v[178:179]
	v_fma_f32 v134, v157, v212, v134
	v_max_f32_e32 v134, 0xda24260, v134
	v_add_f32_e32 v159, 1.0, v159
	v_rcp_f32_e32 v214, v159
	v_log_f32_e32 v134, v134
	v_mul_f32_e32 v159, 0xbfb8aa3b, v181
	v_exp_f32_e32 v159, v159
	v_mul_f32_e32 v157, 0x3f317217, v134
	v_fma_f32 v157, v134, s95, -v157
	v_fmac_f32_e32 v157, 0x3377d1cf, v134
	v_fmac_f32_e32 v157, 0x3f317217, v134
	v_add_f32_e32 v159, 1.0, v159
	v_rcp_f32_e32 v159, v159
	v_mov_b32_e32 v134, v157
	s_nop 0
	v_log_f32_e32 v135, v135
	s_nop 0
	v_mul_f32_e32 v157, 0x3f317217, v135
	v_fma_f32 v157, v135, s95, -v157
	v_fmac_f32_e32 v157, 0x3377d1cf, v135
	v_fmac_f32_e32 v157, 0x3f317217, v135
	s_nop 1
	v_mov_b32_e32 v135, v157
	v_mul_f32_e32 v157, 0xbfb8aa3b, v180
	v_exp_f32_e32 v157, v157
	s_nop 0
	v_add_f32_e32 v157, 1.0, v157
	v_rcp_f32_e32 v157, v157
	s_nop 0
	v_fma_f32 v128, v157, v222, v128
	v_max_f32_e32 v128, 0xda24260, v128
	s_nop 1
	v_log_f32_e32 v128, v128
	s_nop 0
	v_mul_f32_e32 v157, 0x3f317217, v128
	v_fma_f32 v157, v128, s95, -v157
	v_fmac_f32_e32 v157, 0x3377d1cf, v128
	v_fmac_f32_e32 v157, 0x3f317217, v128
	s_nop 1
	v_mov_b32_e32 v128, v157
	v_mov_b32_e32 v218, v128
	v_fma_f32 v128, v159, v223, v129
	v_max_f32_e32 v128, 0xda24260, v128
	s_nop 1
	v_log_f32_e32 v128, v128
	s_nop 0
	v_mul_f32_e32 v129, 0x3f317217, v128
	v_fma_f32 v129, v128, s95, -v129
	v_fmac_f32_e32 v129, 0x3377d1cf, v128
	v_fmac_f32_e32 v129, 0x3f317217, v128
	s_nop 1
	v_mov_b32_e32 v128, v129
	v_mov_b32_e32 v219, v128
	v_mul_f32_e32 v128, 0xbfb8aa3b, v204
	v_exp_f32_e32 v128, v128
	v_mul_f32_e32 v129, 0xbfb8aa3b, v205
	v_exp_f32_e32 v129, v129
	v_add_f32_e32 v128, 1.0, v128
	v_rcp_f32_e32 v157, v128
	v_add_f32_e32 v129, 1.0, v129
	v_rcp_f32_e32 v159, v129
	v_mul_f32_e32 v128, 0x3fb8aa3b, v204
	v_fma_f32 v130, v157, v230, v130
	v_max_f32_e32 v130, 0xda24260, v130
	v_fmac_f32_e32 v131, v159, v231
	v_mul_f32_e32 v129, 0x3fb8aa3b, v205
	v_log_f32_e32 v130, v130
	v_exp_f32_e32 v128, v128
	v_exp_f32_e32 v129, v129
	v_mul_f32_e32 v157, 0x3f317217, v130
	v_fma_f32 v157, v130, s95, -v157
	v_fmac_f32_e32 v157, 0x3377d1cf, v130
	v_fmac_f32_e32 v157, 0x3f317217, v130
	v_add_f32_e32 v128, 1.0, v128
	v_add_f32_e32 v129, 1.0, v129
	v_mov_b32_e32 v130, v157
	v_mov_b32_e32 v220, v130
	v_max_f32_e32 v130, 0xda24260, v131
	v_rcp_f32_e32 v128, v128
	v_rcp_f32_e32 v129, v129
	v_log_f32_e32 v130, v130
	v_pk_mul_f32 v[128:129], v[128:129], v[230:231]
	v_mul_f32_e32 v131, 0x3f317217, v130
	v_fma_f32 v131, v130, s95, -v131
	v_fmac_f32_e32 v131, 0x3377d1cf, v130
	v_fmac_f32_e32 v131, 0x3f317217, v130
	s_nop 1
	v_mov_b32_e32 v130, v131
	v_mov_b32_e32 v221, v130
	v_pk_mul_f32 v[130:131], v[214:215], v[222:223]
	global_store_dwordx4 v[210:211], v[132:135], off
	global_store_dwordx4 v[210:211], v[218:221], off offset:16

.LBB0_300:
	s_andn2_b64 vcc, exec, s[36:37]
	s_cbranch_vccnz .LBB0_302
	global_load_dwordx4 v[120:123], v[148:149], off offset:528
	global_load_dwordx4 v[124:127], v[148:149], off offset:512
	v_mul_f32_e32 v157, 0xbfb8aa3b, v132
	v_exp_f32_e32 v157, v157
	v_mul_f32_e32 v159, 0x3fb8aa3b, v132
	v_exp_f32_e32 v159, v159
	v_mul_f32_e32 v161, 0x3fb8aa3b, v133
	v_add_f32_e32 v157, 1.0, v157
	v_rcp_f32_e32 v157, v157
	v_add_f32_e32 v159, 1.0, v159
	v_rcp_f32_e32 v182, v159
	v_mul_f32_e32 v159, 0xbfb8aa3b, v133
	v_exp_f32_e32 v159, v159
	v_exp_f32_e32 v161, v161
	v_lshl_add_u64 v[178:179], v[150:151], 0, v[178:179]
	v_add_f32_e32 v159, 1.0, v159
	v_rcp_f32_e32 v159, v159
	v_add_f32_e32 v161, 1.0, v161
	v_rcp_f32_e32 v183, v161
	v_mul_f32_e32 v161, 0x3fb8aa3b, v135
	v_exp_f32_e32 v161, v161
	s_waitcnt vmcnt(1)
	v_pk_add_f32 v[214:215], v[120:121], 1.0 op_sel_hi:[1,0] neg_lo:[1,0] neg_hi:[1,0]
	s_waitcnt vmcnt(0)
	v_pk_add_f32 v[202:203], v[124:125], 1.0 op_sel_hi:[1,0] neg_lo:[1,0] neg_hi:[1,0]
	v_pk_add_f32 v[206:207], v[126:127], 1.0 op_sel_hi:[1,0] neg_lo:[1,0] neg_hi:[1,0]
	v_fma_f32 v124, v157, v202, v124
	v_max_f32_e32 v124, 0xda24260, v124
	v_fma_f32 v125, v159, v203, v125
	v_max_f32_e32 v125, 0xda24260, v125
	v_log_f32_e32 v124, v124
	v_mul_f32_e32 v159, 0x3fb8aa3b, v134
	v_exp_f32_e32 v159, v159
	v_pk_add_f32 v[218:219], v[122:123], 1.0 op_sel_hi:[1,0] neg_lo:[1,0] neg_hi:[1,0]
	v_mul_f32_e32 v157, 0x3f317217, v124
	v_fma_f32 v157, v124, s95, -v157
	v_fmac_f32_e32 v157, 0x3377d1cf, v124
	v_fmac_f32_e32 v157, 0x3f317217, v124
	v_add_f32_e32 v159, 1.0, v159
	v_rcp_f32_e32 v204, v159
	v_mov_b32_e32 v124, v157
	v_mul_f32_e32 v159, 0xbfb8aa3b, v135
	v_log_f32_e32 v125, v125
	v_exp_f32_e32 v159, v159
	v_add_f32_e32 v161, 1.0, v161
	v_rcp_f32_e32 v205, v161
	v_mul_f32_e32 v157, 0x3f317217, v125
	v_fma_f32 v157, v125, s95, -v157
	v_fmac_f32_e32 v157, 0x3377d1cf, v125
	v_fmac_f32_e32 v157, 0x3f317217, v125
	v_add_f32_e32 v159, 1.0, v159
	v_rcp_f32_e32 v159, v159
	v_mov_b32_e32 v125, v157
	v_mul_f32_e32 v157, 0xbfb8aa3b, v134
	v_exp_f32_e32 v157, v157
	v_fmac_f32_e32 v127, v159, v207
	v_max_f32_e32 v127, 0xda24260, v127
	v_mul_f32_e32 v159, 0x3fb8aa3b, v130
	v_add_f32_e32 v157, 1.0, v157
	v_rcp_f32_e32 v157, v157
	v_exp_f32_e32 v159, v159
	v_mul_f32_e32 v161, 0x3fb8aa3b, v131
	v_exp_f32_e32 v161, v161
	v_fma_f32 v126, v157, v206, v126
	v_max_f32_e32 v126, 0xda24260, v126
	v_add_f32_e32 v159, 1.0, v159
	v_rcp_f32_e32 v208, v159
	v_log_f32_e32 v126, v126
	v_mul_f32_e32 v159, 0xbfb8aa3b, v131
	v_exp_f32_e32 v159, v159
	v_add_f32_e32 v161, 1.0, v161
	v_mul_f32_e32 v157, 0x3f317217, v126
	v_fma_f32 v157, v126, s95, -v157
	v_fmac_f32_e32 v157, 0x3377d1cf, v126
	v_fmac_f32_e32 v157, 0x3f317217, v126
	v_add_f32_e32 v159, 1.0, v159
	v_rcp_f32_e32 v159, v159
	v_mov_b32_e32 v126, v157
	v_rcp_f32_e32 v209, v161
	v_log_f32_e32 v127, v127
	v_pk_mul_f32 v[202:203], v[182:183], v[202:203]
	v_pk_mul_f32 v[182:183], v[204:205], v[206:207]
	v_mul_f32_e32 v157, 0x3f317217, v127
	v_fma_f32 v157, v127, s95, -v157
	v_fmac_f32_e32 v157, 0x3377d1cf, v127
	v_fmac_f32_e32 v157, 0x3f317217, v127
	s_nop 1
	v_mov_b32_e32 v127, v157
	v_mul_f32_e32 v157, 0xbfb8aa3b, v130
	v_exp_f32_e32 v157, v157
	s_nop 0
	v_add_f32_e32 v157, 1.0, v157
	v_rcp_f32_e32 v157, v157
	s_nop 0
	v_fma_f32 v120, v157, v214, v120
	v_max_f32_e32 v120, 0xda24260, v120
	s_nop 1
	v_log_f32_e32 v120, v120
	s_nop 0
	v_mul_f32_e32 v157, 0x3f317217, v120
	v_fma_f32 v157, v120, s95, -v157
	v_fmac_f32_e32 v157, 0x3377d1cf, v120
	v_fmac_f32_e32 v157, 0x3f317217, v120
	s_nop 1
	v_mov_b32_e32 v120, v157
	v_mov_b32_e32 v210, v120
	v_fma_f32 v120, v159, v215, v121
	v_max_f32_e32 v120, 0xda24260, v120
	s_nop 1
	v_log_f32_e32 v120, v120
	s_nop 0
	v_mul_f32_e32 v121, 0x3f317217, v120
	v_fma_f32 v121, v120, s95, -v121
	v_fmac_f32_e32 v121, 0x3377d1cf, v120
	v_fmac_f32_e32 v121, 0x3f317217, v120
	s_nop 1
	v_mov_b32_e32 v120, v121
	v_mov_b32_e32 v211, v120
	v_mul_f32_e32 v120, 0xbfb8aa3b, v180
	v_exp_f32_e32 v120, v120
	v_mul_f32_e32 v121, 0xbfb8aa3b, v181
	v_exp_f32_e32 v121, v121
	v_add_f32_e32 v120, 1.0, v120
	v_rcp_f32_e32 v157, v120
	v_add_f32_e32 v121, 1.0, v121
	v_rcp_f32_e32 v159, v121
	v_mul_f32_e32 v120, 0x3fb8aa3b, v180
	v_fma_f32 v122, v157, v218, v122
	v_max_f32_e32 v122, 0xda24260, v122
	v_fmac_f32_e32 v123, v159, v219
	v_mul_f32_e32 v121, 0x3fb8aa3b, v181
	v_log_f32_e32 v122, v122
	v_exp_f32_e32 v120, v120
	v_exp_f32_e32 v121, v121
	v_mul_f32_e32 v157, 0x3f317217, v122
	v_fma_f32 v157, v122, s95, -v157
	v_fmac_f32_e32 v157, 0x3377d1cf, v122
	v_fmac_f32_e32 v157, 0x3f317217, v122
	v_add_f32_e32 v120, 1.0, v120
	v_add_f32_e32 v121, 1.0, v121
	v_mov_b32_e32 v122, v157
	v_mov_b32_e32 v212, v122
	v_max_f32_e32 v122, 0xda24260, v123
	v_rcp_f32_e32 v120, v120
	v_rcp_f32_e32 v121, v121
	v_log_f32_e32 v122, v122
	v_pk_mul_f32 v[120:121], v[120:121], v[218:219]
	v_mul_f32_e32 v123, 0x3f317217, v122
	v_fma_f32 v123, v122, s95, -v123
	v_fmac_f32_e32 v123, 0x3377d1cf, v122
	v_fmac_f32_e32 v123, 0x3f317217, v122
	s_nop 1
	v_mov_b32_e32 v122, v123
	v_mov_b32_e32 v213, v122
	v_pk_mul_f32 v[122:123], v[208:209], v[214:215]
	global_store_dwordx4 v[178:179], v[124:127], off
	global_store_dwordx4 v[178:179], v[210:213], off offset:16

.LBB0_312:
	s_andn2_b64 vcc, exec, s[36:37]
	s_cbranch_vccnz .LBB0_314
	v_mul_f32_e32 v120, 0xbfb8aa3b, v134
	v_exp_f32_e32 v120, v120
	v_mul_f32_e32 v159, 0x3fb8aa3b, v179
	v_exp_f32_e32 v159, v159
	v_add_f32_e32 v120, 1.0, v120
	v_rcp_f32_e32 v131, v120
	v_mul_f32_e32 v120, 0x3fb8aa3b, v134
	v_exp_f32_e32 v120, v120
	v_add_f32_e32 v159, 1.0, v159
	v_rcp_f32_e32 v205, v159
	v_mul_f32_e32 v159, 0x3fb8aa3b, v133
	v_add_f32_e32 v120, 1.0, v120
	v_rcp_f32_e32 v182, v120
	v_mul_f32_e32 v120, 0xbfb8aa3b, v135
	v_exp_f32_e32 v120, v120
	v_exp_f32_e32 v159, v159
	v_add_f32_e32 v120, 1.0, v120
	v_rcp_f32_e32 v157, v120
	v_mul_f32_e32 v120, 0x3fb8aa3b, v135
	v_exp_f32_e32 v120, v120
	v_add_f32_e32 v159, 1.0, v159
	v_rcp_f32_e32 v209, v159
	v_add_f32_e32 v120, 1.0, v120
	v_rcp_f32_e32 v183, v120
	global_load_dwordx4 v[120:123], v[148:149], off offset:16
	global_load_dwordx4 v[124:127], v[148:149], off
	s_waitcnt vmcnt(1)
	v_pk_add_f32 v[214:215], v[120:121], 1.0 op_sel_hi:[1,0] neg_lo:[1,0] neg_hi:[1,0]
	s_waitcnt vmcnt(0)
	v_pk_add_f32 v[202:203], v[124:125], 1.0 op_sel_hi:[1,0] neg_lo:[1,0] neg_hi:[1,0]
	v_pk_add_f32 v[206:207], v[126:127], 1.0 op_sel_hi:[1,0] neg_lo:[1,0] neg_hi:[1,0]
	v_fma_f32 v124, v131, v202, v124
	v_max_f32_e32 v124, 0xda24260, v124
	v_fma_f32 v125, v157, v203, v125
	v_max_f32_e32 v125, 0xda24260, v125
	v_log_f32_e32 v124, v124
	v_mul_f32_e32 v157, 0x3fb8aa3b, v178
	v_exp_f32_e32 v157, v157
	v_pk_add_f32 v[218:219], v[122:123], 1.0 op_sel_hi:[1,0] neg_lo:[1,0] neg_hi:[1,0]
	v_mul_f32_e32 v131, 0x3f317217, v124
	v_fma_f32 v131, v124, s95, -v131
	v_fmac_f32_e32 v131, 0x3377d1cf, v124
	v_fmac_f32_e32 v131, 0x3f317217, v124
	v_add_f32_e32 v157, 1.0, v157
	v_rcp_f32_e32 v204, v157
	v_mov_b32_e32 v124, v131
	v_mul_f32_e32 v157, 0xbfb8aa3b, v179
	v_log_f32_e32 v125, v125
	v_exp_f32_e32 v157, v157
	v_pk_mul_f32 v[202:203], v[182:183], v[202:203]
	v_pk_mul_f32 v[182:183], v[204:205], v[206:207]
	v_mul_f32_e32 v131, 0x3f317217, v125
	v_fma_f32 v131, v125, s95, -v131
	v_fmac_f32_e32 v131, 0x3377d1cf, v125
	v_fmac_f32_e32 v131, 0x3f317217, v125
	v_add_f32_e32 v157, 1.0, v157
	v_rcp_f32_e32 v157, v157
	v_mov_b32_e32 v125, v131
	v_mul_f32_e32 v131, 0xbfb8aa3b, v178
	v_exp_f32_e32 v131, v131
	v_fmac_f32_e32 v127, v157, v207
	v_max_f32_e32 v127, 0xda24260, v127
	v_mul_f32_e32 v157, 0x3fb8aa3b, v132
	v_add_f32_e32 v131, 1.0, v131
	v_rcp_f32_e32 v131, v131
	v_exp_f32_e32 v157, v157
	v_lshl_add_u64 v[204:205], v[146:147], 0, v[128:129]
	v_fma_f32 v126, v131, v206, v126
	v_max_f32_e32 v126, 0xda24260, v126
	v_add_f32_e32 v157, 1.0, v157
	v_rcp_f32_e32 v208, v157
	v_log_f32_e32 v126, v126
	v_mul_f32_e32 v157, 0xbfb8aa3b, v133
	v_exp_f32_e32 v157, v157
	v_mul_f32_e32 v131, 0x3f317217, v126
	v_fma_f32 v131, v126, s95, -v131
	v_fmac_f32_e32 v131, 0x3377d1cf, v126
	v_fmac_f32_e32 v131, 0x3f317217, v126
	v_add_f32_e32 v157, 1.0, v157
	v_rcp_f32_e32 v157, v157
	v_mov_b32_e32 v126, v131
	s_nop 0
	v_log_f32_e32 v127, v127
	s_nop 0
	v_mul_f32_e32 v131, 0x3f317217, v127
	v_fma_f32 v131, v127, s95, -v131
	v_fmac_f32_e32 v131, 0x3377d1cf, v127
	v_fmac_f32_e32 v131, 0x3f317217, v127
	s_nop 1
	v_mov_b32_e32 v127, v131
	v_mul_f32_e32 v131, 0xbfb8aa3b, v132
	v_exp_f32_e32 v131, v131
	s_nop 0
	v_add_f32_e32 v131, 1.0, v131
	v_rcp_f32_e32 v131, v131
	s_nop 0
	v_fma_f32 v120, v131, v214, v120
	v_max_f32_e32 v120, 0xda24260, v120
	s_nop 1
	v_log_f32_e32 v120, v120
	s_nop 0
	v_mul_f32_e32 v131, 0x3f317217, v120
	v_fma_f32 v131, v120, s95, -v131
	v_fmac_f32_e32 v131, 0x3377d1cf, v120
	v_fmac_f32_e32 v131, 0x3f317217, v120
	s_nop 1
	v_mov_b32_e32 v120, v131
	v_mov_b32_e32 v210, v120
	v_fma_f32 v120, v157, v215, v121
	v_max_f32_e32 v120, 0xda24260, v120
	s_nop 1
	v_log_f32_e32 v120, v120
	s_nop 0
	v_mul_f32_e32 v121, 0x3f317217, v120
	v_fma_f32 v121, v120, s95, -v121
	v_fmac_f32_e32 v121, 0x3377d1cf, v120
	v_fmac_f32_e32 v121, 0x3f317217, v120
	s_nop 1
	v_mov_b32_e32 v120, v121
	v_mov_b32_e32 v211, v120
	v_mul_f32_e32 v120, 0xbfb8aa3b, v180
	v_exp_f32_e32 v120, v120
	v_mul_f32_e32 v121, 0xbfb8aa3b, v181
	v_exp_f32_e32 v121, v121
	v_add_f32_e32 v120, 1.0, v120
	v_rcp_f32_e32 v131, v120
	v_add_f32_e32 v121, 1.0, v121
	v_rcp_f32_e32 v157, v121
	v_mul_f32_e32 v120, 0x3fb8aa3b, v180
	v_fma_f32 v122, v131, v218, v122
	v_max_f32_e32 v122, 0xda24260, v122
	v_fmac_f32_e32 v123, v157, v219
	v_mul_f32_e32 v121, 0x3fb8aa3b, v181
	v_log_f32_e32 v122, v122
	v_exp_f32_e32 v120, v120
	v_exp_f32_e32 v121, v121
	v_mul_f32_e32 v131, 0x3f317217, v122
	v_fma_f32 v131, v122, s95, -v131
	v_fmac_f32_e32 v131, 0x3377d1cf, v122
	v_fmac_f32_e32 v131, 0x3f317217, v122
	v_add_f32_e32 v120, 1.0, v120
	v_add_f32_e32 v121, 1.0, v121
	v_mov_b32_e32 v122, v131
	v_mov_b32_e32 v212, v122
	v_max_f32_e32 v122, 0xda24260, v123
	v_rcp_f32_e32 v120, v120
	v_rcp_f32_e32 v121, v121
	v_log_f32_e32 v122, v122
	v_pk_mul_f32 v[120:121], v[120:121], v[218:219]
	v_mul_f32_e32 v123, 0x3f317217, v122
	v_fma_f32 v123, v122, s95, -v123
	v_fmac_f32_e32 v123, 0x3377d1cf, v122
	v_fmac_f32_e32 v123, 0x3f317217, v122
	s_nop 1
	v_mov_b32_e32 v122, v123
	v_mov_b32_e32 v213, v122
	v_pk_mul_f32 v[122:123], v[208:209], v[214:215]
	global_store_dwordx4 v[204:205], v[124:127], off
	global_store_dwordx4 v[204:205], v[210:213], off offset:16

.LBB0_324:
	s_andn2_b64 vcc, exec, s[36:37]
	s_cbranch_vccnz .LBB0_326
	global_load_dwordx4 v[112:115], v[148:149], off offset:528
	global_load_dwordx4 v[116:119], v[148:149], off offset:512
	v_mul_f32_e32 v132, 0xbfb8aa3b, v124
	v_exp_f32_e32 v132, v132
	v_mul_f32_e32 v133, 0xbfb8aa3b, v125
	v_exp_f32_e32 v133, v133
	v_mul_f32_e32 v161, 0x3fb8aa3b, v127
	v_add_f32_e32 v132, 1.0, v132
	v_rcp_f32_e32 v157, v132
	v_add_f32_e32 v133, 1.0, v133
	v_rcp_f32_e32 v159, v133
	v_exp_f32_e32 v161, v161
	v_mul_f32_e32 v132, 0x3fb8aa3b, v124
	v_mul_f32_e32 v133, 0x3fb8aa3b, v125
	v_exp_f32_e32 v132, v132
	v_add_f32_e32 v161, 1.0, v161
	v_rcp_f32_e32 v179, v161
	v_mul_f32_e32 v161, 0x3fb8aa3b, v123
	v_exp_f32_e32 v133, v133
	v_exp_f32_e32 v161, v161
	v_add_f32_e32 v132, 1.0, v132
	v_rcp_f32_e32 v132, v132
	v_add_f32_e32 v133, 1.0, v133
	v_add_f32_e32 v161, 1.0, v161
	v_rcp_f32_e32 v133, v133
	v_rcp_f32_e32 v183, v161
	v_lshl_add_u64 v[128:129], v[150:151], 0, v[128:129]
	s_waitcnt vmcnt(1)
	v_pk_add_f32 v[206:207], v[112:113], 1.0 op_sel_hi:[1,0] neg_lo:[1,0] neg_hi:[1,0]
	s_waitcnt vmcnt(0)
	v_pk_add_f32 v[134:135], v[116:117], 1.0 op_sel_hi:[1,0] neg_lo:[1,0] neg_hi:[1,0]
	v_pk_add_f32 v[180:181], v[118:119], 1.0 op_sel_hi:[1,0] neg_lo:[1,0] neg_hi:[1,0]
	v_fma_f32 v116, v157, v134, v116
	v_max_f32_e32 v116, 0xda24260, v116
	v_fma_f32 v117, v159, v135, v117
	v_max_f32_e32 v117, 0xda24260, v117
	v_log_f32_e32 v116, v116
	v_mul_f32_e32 v159, 0x3fb8aa3b, v126
	v_exp_f32_e32 v159, v159
	v_pk_add_f32 v[208:209], v[114:115], 1.0 op_sel_hi:[1,0] neg_lo:[1,0] neg_hi:[1,0]
	v_mul_f32_e32 v157, 0x3f317217, v116
	v_fma_f32 v157, v116, s95, -v157
	v_fmac_f32_e32 v157, 0x3377d1cf, v116
	v_fmac_f32_e32 v157, 0x3f317217, v116
	v_add_f32_e32 v159, 1.0, v159
	v_rcp_f32_e32 v178, v159
	v_mov_b32_e32 v116, v157
	v_mul_f32_e32 v159, 0xbfb8aa3b, v127
	v_log_f32_e32 v117, v117
	v_exp_f32_e32 v159, v159
	v_pk_mul_f32 v[134:135], v[132:133], v[134:135]
	v_pk_mul_f32 v[132:133], v[178:179], v[180:181]
	v_mul_f32_e32 v157, 0x3f317217, v117
	v_fma_f32 v157, v117, s95, -v157
	v_fmac_f32_e32 v157, 0x3377d1cf, v117
	v_fmac_f32_e32 v157, 0x3f317217, v117
	v_add_f32_e32 v159, 1.0, v159
	v_rcp_f32_e32 v159, v159
	v_mov_b32_e32 v117, v157
	v_mul_f32_e32 v157, 0xbfb8aa3b, v126
	v_exp_f32_e32 v157, v157
	v_fmac_f32_e32 v119, v159, v181
	v_max_f32_e32 v119, 0xda24260, v119
	v_mul_f32_e32 v159, 0x3fb8aa3b, v122
	v_add_f32_e32 v157, 1.0, v157
	v_rcp_f32_e32 v157, v157
	v_exp_f32_e32 v159, v159
	v_fma_f32 v118, v157, v180, v118
	v_max_f32_e32 v118, 0xda24260, v118
	v_add_f32_e32 v159, 1.0, v159
	v_rcp_f32_e32 v182, v159
	v_log_f32_e32 v118, v118
	v_mul_f32_e32 v159, 0xbfb8aa3b, v123
	v_exp_f32_e32 v159, v159
	v_mul_f32_e32 v157, 0x3f317217, v118
	v_fma_f32 v157, v118, s95, -v157
	v_fmac_f32_e32 v157, 0x3377d1cf, v118
	v_fmac_f32_e32 v157, 0x3f317217, v118
	v_add_f32_e32 v159, 1.0, v159
	v_rcp_f32_e32 v159, v159
	v_mov_b32_e32 v118, v157
	s_nop 0
	v_log_f32_e32 v119, v119
	s_nop 0
	v_mul_f32_e32 v157, 0x3f317217, v119
	v_fma_f32 v157, v119, s95, -v157
	v_fmac_f32_e32 v157, 0x3377d1cf, v119
	v_fmac_f32_e32 v157, 0x3f317217, v119
	s_nop 1
	v_mov_b32_e32 v119, v157
	v_mul_f32_e32 v157, 0xbfb8aa3b, v122
	v_exp_f32_e32 v157, v157
	s_nop 0
	v_add_f32_e32 v157, 1.0, v157
	v_rcp_f32_e32 v157, v157
	s_nop 0
	v_fma_f32 v112, v157, v206, v112
	v_max_f32_e32 v112, 0xda24260, v112
	s_nop 1
	v_log_f32_e32 v112, v112
	s_nop 0
	v_mul_f32_e32 v157, 0x3f317217, v112
	v_fma_f32 v157, v112, s95, -v157
	v_fmac_f32_e32 v157, 0x3377d1cf, v112
	v_fmac_f32_e32 v157, 0x3f317217, v112
	s_nop 1
	v_mov_b32_e32 v112, v157
	v_mov_b32_e32 v202, v112
	v_fma_f32 v112, v159, v207, v113
	v_max_f32_e32 v112, 0xda24260, v112
	s_nop 1
	v_log_f32_e32 v112, v112
	s_nop 0
	v_mul_f32_e32 v113, 0x3f317217, v112
	v_fma_f32 v113, v112, s95, -v113
	v_fmac_f32_e32 v113, 0x3377d1cf, v112
	v_fmac_f32_e32 v113, 0x3f317217, v112
	s_nop 1
	v_mov_b32_e32 v112, v113
	v_mov_b32_e32 v203, v112
	v_mul_f32_e32 v112, 0xbfb8aa3b, v130
	v_exp_f32_e32 v112, v112
	v_mul_f32_e32 v113, 0xbfb8aa3b, v131
	v_exp_f32_e32 v113, v113
	v_add_f32_e32 v112, 1.0, v112
	v_rcp_f32_e32 v157, v112
	v_add_f32_e32 v113, 1.0, v113
	v_rcp_f32_e32 v159, v113
	v_mul_f32_e32 v112, 0x3fb8aa3b, v130
	v_fma_f32 v114, v157, v208, v114
	v_max_f32_e32 v114, 0xda24260, v114
	v_fmac_f32_e32 v115, v159, v209
	v_mul_f32_e32 v113, 0x3fb8aa3b, v131
	v_log_f32_e32 v114, v114
	v_exp_f32_e32 v112, v112
	v_exp_f32_e32 v113, v113
	v_mul_f32_e32 v157, 0x3f317217, v114
	v_fma_f32 v157, v114, s95, -v157
	v_fmac_f32_e32 v157, 0x3377d1cf, v114
	v_fmac_f32_e32 v157, 0x3f317217, v114
	v_add_f32_e32 v112, 1.0, v112
	v_add_f32_e32 v113, 1.0, v113
	v_mov_b32_e32 v114, v157
	v_mov_b32_e32 v204, v114
	v_max_f32_e32 v114, 0xda24260, v115
	v_rcp_f32_e32 v112, v112
	v_rcp_f32_e32 v113, v113
	v_log_f32_e32 v114, v114
	v_pk_mul_f32 v[112:113], v[112:113], v[208:209]
	v_mul_f32_e32 v115, 0x3f317217, v114
	v_fma_f32 v115, v114, s95, -v115
	v_fmac_f32_e32 v115, 0x3377d1cf, v114
	v_fmac_f32_e32 v115, 0x3f317217, v114
	s_nop 1
	v_mov_b32_e32 v114, v115
	v_mov_b32_e32 v205, v114
	v_pk_mul_f32 v[114:115], v[182:183], v[206:207]
	global_store_dwordx4 v[128:129], v[116:119], off
	global_store_dwordx4 v[128:129], v[202:205], off offset:16

.LBB0_336:
	s_andn2_b64 vcc, exec, s[36:37]
	s_cbranch_vccnz .LBB0_338
	v_mul_f32_e32 v112, 0xbfb8aa3b, v126
	v_exp_f32_e32 v112, v112
	v_mul_f32_e32 v159, 0x3fb8aa3b, v129
	v_exp_f32_e32 v159, v159
	v_add_f32_e32 v112, 1.0, v112
	v_rcp_f32_e32 v123, v112
	v_mul_f32_e32 v112, 0x3fb8aa3b, v126
	v_exp_f32_e32 v112, v112
	v_add_f32_e32 v159, 1.0, v159
	v_rcp_f32_e32 v179, v159
	v_mul_f32_e32 v159, 0x3fb8aa3b, v125
	v_add_f32_e32 v112, 1.0, v112
	v_rcp_f32_e32 v132, v112
	v_mul_f32_e32 v112, 0xbfb8aa3b, v127
	v_exp_f32_e32 v112, v112
	v_exp_f32_e32 v159, v159
	v_add_f32_e32 v112, 1.0, v112
	v_rcp_f32_e32 v157, v112
	v_mul_f32_e32 v112, 0x3fb8aa3b, v127
	v_exp_f32_e32 v112, v112
	v_add_f32_e32 v159, 1.0, v159
	v_rcp_f32_e32 v183, v159
	v_add_f32_e32 v112, 1.0, v112
	v_rcp_f32_e32 v133, v112
	global_load_dwordx4 v[112:115], v[148:149], off offset:16
	global_load_dwordx4 v[116:119], v[148:149], off
	s_waitcnt vmcnt(1)
	v_pk_add_f32 v[206:207], v[112:113], 1.0 op_sel_hi:[1,0] neg_lo:[1,0] neg_hi:[1,0]
	s_waitcnt vmcnt(0)
	v_pk_add_f32 v[134:135], v[116:117], 1.0 op_sel_hi:[1,0] neg_lo:[1,0] neg_hi:[1,0]
	v_pk_add_f32 v[180:181], v[118:119], 1.0 op_sel_hi:[1,0] neg_lo:[1,0] neg_hi:[1,0]
	v_fma_f32 v116, v123, v134, v116
	v_max_f32_e32 v116, 0xda24260, v116
	v_fma_f32 v117, v157, v135, v117
	v_max_f32_e32 v117, 0xda24260, v117
	v_log_f32_e32 v116, v116
	v_mul_f32_e32 v157, 0x3fb8aa3b, v128
	v_exp_f32_e32 v157, v157
	v_pk_add_f32 v[208:209], v[114:115], 1.0 op_sel_hi:[1,0] neg_lo:[1,0] neg_hi:[1,0]
	v_mul_f32_e32 v123, 0x3f317217, v116
	v_fma_f32 v123, v116, s95, -v123
	v_fmac_f32_e32 v123, 0x3377d1cf, v116
	v_fmac_f32_e32 v123, 0x3f317217, v116
	v_add_f32_e32 v157, 1.0, v157
	v_rcp_f32_e32 v178, v157
	v_mov_b32_e32 v116, v123
	v_mul_f32_e32 v157, 0xbfb8aa3b, v129
	v_log_f32_e32 v117, v117
	v_exp_f32_e32 v157, v157
	v_pk_mul_f32 v[134:135], v[132:133], v[134:135]
	v_pk_mul_f32 v[132:133], v[178:179], v[180:181]
	v_mul_f32_e32 v123, 0x3f317217, v117
	v_fma_f32 v123, v117, s95, -v123
	v_fmac_f32_e32 v123, 0x3377d1cf, v117
	v_fmac_f32_e32 v123, 0x3f317217, v117
	v_add_f32_e32 v157, 1.0, v157
	v_rcp_f32_e32 v157, v157
	v_mov_b32_e32 v117, v123
	v_mul_f32_e32 v123, 0xbfb8aa3b, v128
	v_exp_f32_e32 v123, v123
	v_fmac_f32_e32 v119, v157, v181
	v_max_f32_e32 v119, 0xda24260, v119
	v_mul_f32_e32 v157, 0x3fb8aa3b, v124
	v_add_f32_e32 v123, 1.0, v123
	v_rcp_f32_e32 v123, v123
	v_exp_f32_e32 v157, v157
	v_lshl_add_u64 v[178:179], v[146:147], 0, v[120:121]
	v_fma_f32 v118, v123, v180, v118
	v_max_f32_e32 v118, 0xda24260, v118
	v_add_f32_e32 v157, 1.0, v157
	v_rcp_f32_e32 v182, v157
	v_log_f32_e32 v118, v118
	v_mul_f32_e32 v157, 0xbfb8aa3b, v125
	v_exp_f32_e32 v157, v157
	v_mul_f32_e32 v123, 0x3f317217, v118
	v_fma_f32 v123, v118, s95, -v123
	v_fmac_f32_e32 v123, 0x3377d1cf, v118
	v_fmac_f32_e32 v123, 0x3f317217, v118
	v_add_f32_e32 v157, 1.0, v157
	v_rcp_f32_e32 v157, v157
	v_mov_b32_e32 v118, v123
	s_nop 0
	v_log_f32_e32 v119, v119
	s_nop 0
	v_mul_f32_e32 v123, 0x3f317217, v119
	v_fma_f32 v123, v119, s95, -v123
	v_fmac_f32_e32 v123, 0x3377d1cf, v119
	v_fmac_f32_e32 v123, 0x3f317217, v119
	s_nop 1
	v_mov_b32_e32 v119, v123
	v_mul_f32_e32 v123, 0xbfb8aa3b, v124
	v_exp_f32_e32 v123, v123
	s_nop 0
	v_add_f32_e32 v123, 1.0, v123
	v_rcp_f32_e32 v123, v123
	s_nop 0
	v_fma_f32 v112, v123, v206, v112
	v_max_f32_e32 v112, 0xda24260, v112
	s_nop 1
	v_log_f32_e32 v112, v112
	s_nop 0
	v_mul_f32_e32 v123, 0x3f317217, v112
	v_fma_f32 v123, v112, s95, -v123
	v_fmac_f32_e32 v123, 0x3377d1cf, v112
	v_fmac_f32_e32 v123, 0x3f317217, v112
	s_nop 1
	v_mov_b32_e32 v112, v123
	v_mov_b32_e32 v202, v112
	v_fma_f32 v112, v157, v207, v113
	v_max_f32_e32 v112, 0xda24260, v112
	s_nop 1
	v_log_f32_e32 v112, v112
	s_nop 0
	v_mul_f32_e32 v113, 0x3f317217, v112
	v_fma_f32 v113, v112, s95, -v113
	v_fmac_f32_e32 v113, 0x3377d1cf, v112
	v_fmac_f32_e32 v113, 0x3f317217, v112
	s_nop 1
	v_mov_b32_e32 v112, v113
	v_mov_b32_e32 v203, v112
	v_mul_f32_e32 v112, 0xbfb8aa3b, v130
	v_exp_f32_e32 v112, v112
	v_mul_f32_e32 v113, 0xbfb8aa3b, v131
	v_exp_f32_e32 v113, v113
	v_add_f32_e32 v112, 1.0, v112
	v_rcp_f32_e32 v123, v112
	v_add_f32_e32 v113, 1.0, v113
	v_rcp_f32_e32 v157, v113
	v_mul_f32_e32 v112, 0x3fb8aa3b, v130
	v_fma_f32 v114, v123, v208, v114
	v_max_f32_e32 v114, 0xda24260, v114
	v_fmac_f32_e32 v115, v157, v209
	v_mul_f32_e32 v113, 0x3fb8aa3b, v131
	v_log_f32_e32 v114, v114
	v_exp_f32_e32 v112, v112
	v_exp_f32_e32 v113, v113
	v_mul_f32_e32 v123, 0x3f317217, v114
	v_fma_f32 v123, v114, s95, -v123
	v_fmac_f32_e32 v123, 0x3377d1cf, v114
	v_fmac_f32_e32 v123, 0x3f317217, v114
	v_add_f32_e32 v112, 1.0, v112
	v_add_f32_e32 v113, 1.0, v113
	v_mov_b32_e32 v114, v123
	v_mov_b32_e32 v204, v114
	v_max_f32_e32 v114, 0xda24260, v115
	v_rcp_f32_e32 v112, v112
	v_rcp_f32_e32 v113, v113
	v_log_f32_e32 v114, v114
	v_pk_mul_f32 v[112:113], v[112:113], v[208:209]
	v_mul_f32_e32 v115, 0x3f317217, v114
	v_fma_f32 v115, v114, s95, -v115
	v_fmac_f32_e32 v115, 0x3377d1cf, v114
	v_fmac_f32_e32 v115, 0x3f317217, v114
	s_nop 1
	v_mov_b32_e32 v114, v115
	v_mov_b32_e32 v205, v114
	v_pk_mul_f32 v[114:115], v[182:183], v[206:207]
	global_store_dwordx4 v[178:179], v[116:119], off
	global_store_dwordx4 v[178:179], v[202:205], off offset:16

.LBB0_348:
	s_andn2_b64 vcc, exec, s[36:37]
	s_cbranch_vccnz .LBB0_350
	global_load_dwordx4 v[104:107], v[148:149], off offset:528
	global_load_dwordx4 v[108:111], v[148:149], off offset:512
	v_mul_f32_e32 v124, 0xbfb8aa3b, v116
	v_exp_f32_e32 v124, v124
	v_mul_f32_e32 v125, 0xbfb8aa3b, v117
	v_exp_f32_e32 v125, v125
	v_lshl_add_u64 v[120:121], v[150:151], 0, v[120:121]
	v_add_f32_e32 v124, 1.0, v124
	v_rcp_f32_e32 v128, v124
	v_add_f32_e32 v125, 1.0, v125
	v_rcp_f32_e32 v129, v125
	v_mul_f32_e32 v124, 0x3fb8aa3b, v116
	v_mul_f32_e32 v125, 0x3fb8aa3b, v117
	v_exp_f32_e32 v124, v124
	v_exp_f32_e32 v125, v125
	v_add_f32_e32 v124, 1.0, v124
	v_add_f32_e32 v125, 1.0, v125
	v_rcp_f32_e32 v124, v124
	v_rcp_f32_e32 v125, v125
	s_waitcnt vmcnt(1)
	v_pk_add_f32 v[134:135], v[104:105], 1.0 op_sel_hi:[1,0] neg_lo:[1,0] neg_hi:[1,0]
	s_waitcnt vmcnt(0)
	v_pk_add_f32 v[126:127], v[108:109], 1.0 op_sel_hi:[1,0] neg_lo:[1,0] neg_hi:[1,0]
	v_pk_add_f32 v[130:131], v[110:111], 1.0 op_sel_hi:[1,0] neg_lo:[1,0] neg_hi:[1,0]
	v_fma_f32 v108, v128, v126, v108
	v_max_f32_e32 v108, 0xda24260, v108
	v_fma_f32 v109, v129, v127, v109
	v_max_f32_e32 v109, 0xda24260, v109
	v_log_f32_e32 v108, v108
	v_mul_f32_e32 v129, 0xbfb8aa3b, v119
	v_exp_f32_e32 v129, v129
	v_pk_add_f32 v[182:183], v[106:107], 1.0 op_sel_hi:[1,0] neg_lo:[1,0] neg_hi:[1,0]
	v_mul_f32_e32 v128, 0x3f317217, v108
	v_fma_f32 v128, v108, s95, -v128
	v_fmac_f32_e32 v128, 0x3377d1cf, v108
	v_fmac_f32_e32 v128, 0x3f317217, v108
	v_add_f32_e32 v129, 1.0, v129
	v_rcp_f32_e32 v133, v129
	v_mov_b32_e32 v108, v128
	v_fmac_f32_e32 v111, v133, v131
	v_log_f32_e32 v109, v109
	v_max_f32_e32 v111, 0xda24260, v111
	v_mul_f32_e32 v133, 0xbfb8aa3b, v115
	v_exp_f32_e32 v133, v133
	v_mul_f32_e32 v128, 0x3f317217, v109
	v_fma_f32 v128, v109, s95, -v128
	v_fmac_f32_e32 v128, 0x3377d1cf, v109
	v_fmac_f32_e32 v128, 0x3f317217, v109
	v_add_f32_e32 v133, 1.0, v133
	v_rcp_f32_e32 v159, v133
	v_mov_b32_e32 v109, v128
	v_mul_f32_e32 v128, 0xbfb8aa3b, v118
	v_exp_f32_e32 v128, v128
	v_mul_f32_e32 v129, 0x3fb8aa3b, v119
	v_mul_f32_e32 v133, 0x3fb8aa3b, v115
	v_exp_f32_e32 v129, v129
	v_add_f32_e32 v128, 1.0, v128
	v_rcp_f32_e32 v132, v128
	v_mul_f32_e32 v128, 0x3fb8aa3b, v118
	v_exp_f32_e32 v128, v128
	v_exp_f32_e32 v133, v133
	v_fma_f32 v110, v132, v130, v110
	v_max_f32_e32 v110, 0xda24260, v110
	v_add_f32_e32 v128, 1.0, v128
	v_add_f32_e32 v129, 1.0, v129
	v_log_f32_e32 v110, v110
	v_add_f32_e32 v133, 1.0, v133
	v_rcp_f32_e32 v128, v128
	v_rcp_f32_e32 v129, v129
	v_mul_f32_e32 v132, 0x3f317217, v110
	v_fma_f32 v132, v110, s95, -v132
	v_fmac_f32_e32 v132, 0x3377d1cf, v110
	v_fmac_f32_e32 v132, 0x3f317217, v110
	v_rcp_f32_e32 v133, v133
	v_pk_mul_f32 v[126:127], v[124:125], v[126:127]
	v_mov_b32_e32 v110, v132
	v_pk_mul_f32 v[124:125], v[128:129], v[130:131]
	v_log_f32_e32 v111, v111
	s_nop 0
	v_mul_f32_e32 v132, 0x3f317217, v111
	v_fma_f32 v132, v111, s95, -v132
	v_fmac_f32_e32 v132, 0x3377d1cf, v111
	v_fmac_f32_e32 v132, 0x3f317217, v111
	s_nop 1
	v_mov_b32_e32 v111, v132
	v_mul_f32_e32 v132, 0xbfb8aa3b, v114
	v_exp_f32_e32 v132, v132
	s_nop 0
	v_add_f32_e32 v132, 1.0, v132
	v_rcp_f32_e32 v157, v132
	v_mul_f32_e32 v132, 0x3fb8aa3b, v114
	v_exp_f32_e32 v132, v132
	v_fma_f32 v104, v157, v134, v104
	v_max_f32_e32 v104, 0xda24260, v104
	v_add_f32_e32 v132, 1.0, v132
	v_rcp_f32_e32 v132, v132
	v_log_f32_e32 v104, v104
	s_nop 0
	v_mul_f32_e32 v157, 0x3f317217, v104
	v_fma_f32 v157, v104, s95, -v157
	v_fmac_f32_e32 v157, 0x3377d1cf, v104
	v_fmac_f32_e32 v157, 0x3f317217, v104
	s_nop 1
	v_mov_b32_e32 v104, v157
	v_mov_b32_e32 v178, v104
	v_fma_f32 v104, v159, v135, v105
	v_max_f32_e32 v104, 0xda24260, v104
	s_nop 1
	v_log_f32_e32 v104, v104
	s_nop 0
	v_mul_f32_e32 v105, 0x3f317217, v104
	v_fma_f32 v105, v104, s95, -v105
	v_fmac_f32_e32 v105, 0x3377d1cf, v104
	v_fmac_f32_e32 v105, 0x3f317217, v104
	s_nop 1
	v_mov_b32_e32 v104, v105
	v_mov_b32_e32 v179, v104
	v_mul_f32_e32 v104, 0xbfb8aa3b, v122
	v_exp_f32_e32 v104, v104
	v_mul_f32_e32 v105, 0xbfb8aa3b, v123
	v_exp_f32_e32 v105, v105
	v_add_f32_e32 v104, 1.0, v104
	v_rcp_f32_e32 v157, v104
	v_add_f32_e32 v105, 1.0, v105
	v_rcp_f32_e32 v159, v105
	v_mul_f32_e32 v104, 0x3fb8aa3b, v122
	v_fma_f32 v106, v157, v182, v106
	v_max_f32_e32 v106, 0xda24260, v106
	v_fmac_f32_e32 v107, v159, v183
	v_mul_f32_e32 v105, 0x3fb8aa3b, v123
	v_log_f32_e32 v106, v106
	v_exp_f32_e32 v104, v104
	v_exp_f32_e32 v105, v105
	v_mul_f32_e32 v157, 0x3f317217, v106
	v_fma_f32 v157, v106, s95, -v157
	v_fmac_f32_e32 v157, 0x3377d1cf, v106
	v_fmac_f32_e32 v157, 0x3f317217, v106
	v_add_f32_e32 v104, 1.0, v104
	v_add_f32_e32 v105, 1.0, v105
	v_mov_b32_e32 v106, v157
	v_mov_b32_e32 v180, v106
	v_max_f32_e32 v106, 0xda24260, v107
	v_rcp_f32_e32 v104, v104
	v_rcp_f32_e32 v105, v105
	v_log_f32_e32 v106, v106
	v_pk_mul_f32 v[104:105], v[104:105], v[182:183]
	v_mul_f32_e32 v107, 0x3f317217, v106
	v_fma_f32 v107, v106, s95, -v107
	v_fmac_f32_e32 v107, 0x3377d1cf, v106
	v_fmac_f32_e32 v107, 0x3f317217, v106
	s_nop 1
	v_mov_b32_e32 v106, v107
	v_mov_b32_e32 v181, v106
	v_pk_mul_f32 v[106:107], v[132:133], v[134:135]
	global_store_dwordx4 v[120:121], v[108:111], off
	global_store_dwordx4 v[120:121], v[178:181], off offset:16

.LBB0_360:
	s_andn2_b64 vcc, exec, s[36:37]
	s_cbranch_vccnz .LBB0_362
	v_mul_f32_e32 v104, 0xbfb8aa3b, v118
	v_exp_f32_e32 v104, v104
	v_mul_f32_e32 v129, 0xbfb8aa3b, v121
	v_exp_f32_e32 v129, v129
	v_mul_f32_e32 v133, 0xbfb8aa3b, v117
	v_add_f32_e32 v104, 1.0, v104
	v_rcp_f32_e32 v115, v104
	v_mul_f32_e32 v104, 0x3fb8aa3b, v118
	v_exp_f32_e32 v104, v104
	v_add_f32_e32 v129, 1.0, v129
	v_rcp_f32_e32 v132, v129
	v_exp_f32_e32 v133, v133
	v_add_f32_e32 v104, 1.0, v104
	v_rcp_f32_e32 v124, v104
	v_mul_f32_e32 v104, 0xbfb8aa3b, v119
	v_exp_f32_e32 v104, v104
	v_add_f32_e32 v133, 1.0, v133
	v_rcp_f32_e32 v157, v133
	v_mul_f32_e32 v129, 0x3fb8aa3b, v121
	v_add_f32_e32 v104, 1.0, v104
	v_rcp_f32_e32 v128, v104
	v_mul_f32_e32 v104, 0x3fb8aa3b, v119
	v_exp_f32_e32 v104, v104
	v_mul_f32_e32 v133, 0x3fb8aa3b, v117
	v_exp_f32_e32 v129, v129
	v_exp_f32_e32 v133, v133
	v_add_f32_e32 v104, 1.0, v104
	v_rcp_f32_e32 v125, v104
	global_load_dwordx4 v[104:107], v[148:149], off offset:16
	global_load_dwordx4 v[108:111], v[148:149], off
	v_add_f32_e32 v129, 1.0, v129
	v_add_f32_e32 v133, 1.0, v133
	v_rcp_f32_e32 v129, v129
	v_rcp_f32_e32 v133, v133
	s_waitcnt vmcnt(1)
	v_pk_add_f32 v[134:135], v[104:105], 1.0 op_sel_hi:[1,0] neg_lo:[1,0] neg_hi:[1,0]
	s_waitcnt vmcnt(0)
	v_pk_add_f32 v[126:127], v[108:109], 1.0 op_sel_hi:[1,0] neg_lo:[1,0] neg_hi:[1,0]
	v_pk_add_f32 v[130:131], v[110:111], 1.0 op_sel_hi:[1,0] neg_lo:[1,0] neg_hi:[1,0]
	v_fma_f32 v108, v115, v126, v108
	v_max_f32_e32 v108, 0xda24260, v108
	v_fma_f32 v109, v128, v127, v109
	v_max_f32_e32 v109, 0xda24260, v109
	v_log_f32_e32 v108, v108
	v_fmac_f32_e32 v111, v132, v131
	v_max_f32_e32 v111, 0xda24260, v111
	v_pk_add_f32 v[182:183], v[106:107], 1.0 op_sel_hi:[1,0] neg_lo:[1,0] neg_hi:[1,0]
	v_mul_f32_e32 v115, 0x3f317217, v108
	v_fma_f32 v115, v108, s95, -v115
	v_fmac_f32_e32 v115, 0x3377d1cf, v108
	v_fmac_f32_e32 v115, 0x3f317217, v108
	v_mul_f32_e32 v128, 0x3fb8aa3b, v120
	v_mul_f32_e32 v132, 0x3fb8aa3b, v116
	v_mov_b32_e32 v108, v115
	v_exp_f32_e32 v128, v128
	v_log_f32_e32 v109, v109
	v_exp_f32_e32 v132, v132
	v_add_f32_e32 v128, 1.0, v128
	v_rcp_f32_e32 v128, v128
	v_mul_f32_e32 v115, 0x3f317217, v109
	v_fma_f32 v115, v109, s95, -v115
	v_fmac_f32_e32 v115, 0x3377d1cf, v109
	v_fmac_f32_e32 v115, 0x3f317217, v109
	v_add_f32_e32 v132, 1.0, v132
	v_rcp_f32_e32 v132, v132
	v_mov_b32_e32 v109, v115
	v_mul_f32_e32 v115, 0xbfb8aa3b, v120
	v_exp_f32_e32 v115, v115
	v_pk_mul_f32 v[126:127], v[124:125], v[126:127]
	v_pk_mul_f32 v[124:125], v[128:129], v[130:131]
	v_lshl_add_u64 v[128:129], v[146:147], 0, v[112:113]
	v_add_f32_e32 v115, 1.0, v115
	v_rcp_f32_e32 v115, v115
	s_nop 0
	v_fma_f32 v110, v115, v130, v110
	v_max_f32_e32 v110, 0xda24260, v110
	s_nop 1
	v_log_f32_e32 v110, v110
	s_nop 0
	v_mul_f32_e32 v115, 0x3f317217, v110
	v_fma_f32 v115, v110, s95, -v115
	v_fmac_f32_e32 v115, 0x3377d1cf, v110
	v_fmac_f32_e32 v115, 0x3f317217, v110
	s_nop 1
	v_mov_b32_e32 v110, v115
	s_nop 0
	v_log_f32_e32 v111, v111
	s_nop 0
	v_mul_f32_e32 v115, 0x3f317217, v111
	v_fma_f32 v115, v111, s95, -v115
	v_fmac_f32_e32 v115, 0x3377d1cf, v111
	v_fmac_f32_e32 v115, 0x3f317217, v111
	s_nop 1
	v_mov_b32_e32 v111, v115
	v_mul_f32_e32 v115, 0xbfb8aa3b, v116
	v_exp_f32_e32 v115, v115
	s_nop 0
	v_add_f32_e32 v115, 1.0, v115
	v_rcp_f32_e32 v115, v115
	s_nop 0
	v_fma_f32 v104, v115, v134, v104
	v_max_f32_e32 v104, 0xda24260, v104
	s_nop 1
	v_log_f32_e32 v104, v104
	s_nop 0
	v_mul_f32_e32 v115, 0x3f317217, v104
	v_fma_f32 v115, v104, s95, -v115
	v_fmac_f32_e32 v115, 0x3377d1cf, v104
	v_fmac_f32_e32 v115, 0x3f317217, v104
	s_nop 1
	v_mov_b32_e32 v104, v115
	v_mov_b32_e32 v178, v104
	v_fma_f32 v104, v157, v135, v105
	v_max_f32_e32 v104, 0xda24260, v104
	s_nop 1
	v_log_f32_e32 v104, v104
	s_nop 0
	v_mul_f32_e32 v105, 0x3f317217, v104
	v_fma_f32 v105, v104, s95, -v105
	v_fmac_f32_e32 v105, 0x3377d1cf, v104
	v_fmac_f32_e32 v105, 0x3f317217, v104
	s_nop 1
	v_mov_b32_e32 v104, v105
	v_mov_b32_e32 v179, v104
	v_mul_f32_e32 v104, 0xbfb8aa3b, v122
	v_exp_f32_e32 v104, v104
	v_mul_f32_e32 v105, 0xbfb8aa3b, v123
	v_exp_f32_e32 v105, v105
	v_add_f32_e32 v104, 1.0, v104
	v_rcp_f32_e32 v115, v104
	v_add_f32_e32 v105, 1.0, v105
	v_rcp_f32_e32 v157, v105
	v_mul_f32_e32 v104, 0x3fb8aa3b, v122
	v_fma_f32 v106, v115, v182, v106
	v_max_f32_e32 v106, 0xda24260, v106
	v_fmac_f32_e32 v107, v157, v183
	v_mul_f32_e32 v105, 0x3fb8aa3b, v123
	v_log_f32_e32 v106, v106
	v_exp_f32_e32 v104, v104
	v_exp_f32_e32 v105, v105
	v_mul_f32_e32 v115, 0x3f317217, v106
	v_fma_f32 v115, v106, s95, -v115
	v_fmac_f32_e32 v115, 0x3377d1cf, v106
	v_fmac_f32_e32 v115, 0x3f317217, v106
	v_add_f32_e32 v104, 1.0, v104
	v_add_f32_e32 v105, 1.0, v105
	v_mov_b32_e32 v106, v115
	v_mov_b32_e32 v180, v106
	v_max_f32_e32 v106, 0xda24260, v107
	v_rcp_f32_e32 v104, v104
	v_rcp_f32_e32 v105, v105
	v_log_f32_e32 v106, v106
	v_pk_mul_f32 v[104:105], v[104:105], v[182:183]
	v_mul_f32_e32 v107, 0x3f317217, v106
	v_fma_f32 v107, v106, s95, -v107
	v_fmac_f32_e32 v107, 0x3377d1cf, v106
	v_fmac_f32_e32 v107, 0x3f317217, v106
	s_nop 1
	v_mov_b32_e32 v106, v107
	v_mov_b32_e32 v181, v106
	v_pk_mul_f32 v[106:107], v[132:133], v[134:135]
	global_store_dwordx4 v[128:129], v[108:111], off
	global_store_dwordx4 v[128:129], v[178:181], off offset:16

.LBB0_372:
	s_andn2_b64 vcc, exec, s[36:37]
	s_cbranch_vccnz .LBB0_374
	global_load_dwordx4 v[96:99], v[148:149], off offset:528
	global_load_dwordx4 v[100:103], v[148:149], off offset:512
	v_mul_f32_e32 v116, 0xbfb8aa3b, v108
	v_exp_f32_e32 v116, v116
	v_mul_f32_e32 v117, 0xbfb8aa3b, v109
	v_exp_f32_e32 v117, v117
	v_lshl_add_u64 v[112:113], v[150:151], 0, v[112:113]
	v_add_f32_e32 v116, 1.0, v116
	v_rcp_f32_e32 v120, v116
	v_add_f32_e32 v117, 1.0, v117
	v_rcp_f32_e32 v121, v117
	v_mul_f32_e32 v116, 0x3fb8aa3b, v108
	v_mul_f32_e32 v117, 0x3fb8aa3b, v109
	v_exp_f32_e32 v116, v116
	v_exp_f32_e32 v117, v117
	v_add_f32_e32 v116, 1.0, v116
	v_add_f32_e32 v117, 1.0, v117
	v_rcp_f32_e32 v116, v116
	v_rcp_f32_e32 v117, v117
	s_waitcnt vmcnt(1)
	v_pk_add_f32 v[130:131], v[96:97], 1.0 op_sel_hi:[1,0] neg_lo:[1,0] neg_hi:[1,0]
	s_waitcnt vmcnt(0)
	v_pk_add_f32 v[118:119], v[100:101], 1.0 op_sel_hi:[1,0] neg_lo:[1,0] neg_hi:[1,0]
	v_pk_add_f32 v[122:123], v[102:103], 1.0 op_sel_hi:[1,0] neg_lo:[1,0] neg_hi:[1,0]
	v_fma_f32 v100, v120, v118, v100
	v_max_f32_e32 v100, 0xda24260, v100
	v_fma_f32 v101, v121, v119, v101
	v_max_f32_e32 v101, 0xda24260, v101
	v_log_f32_e32 v100, v100
	v_mul_f32_e32 v121, 0xbfb8aa3b, v111
	v_exp_f32_e32 v121, v121
	v_pk_add_f32 v[132:133], v[98:99], 1.0 op_sel_hi:[1,0] neg_lo:[1,0] neg_hi:[1,0]
	v_mul_f32_e32 v120, 0x3f317217, v100
	v_fma_f32 v120, v100, s95, -v120
	v_fmac_f32_e32 v120, 0x3377d1cf, v100
	v_fmac_f32_e32 v120, 0x3f317217, v100
	v_add_f32_e32 v121, 1.0, v121
	v_rcp_f32_e32 v125, v121
	v_mov_b32_e32 v100, v120
	v_fmac_f32_e32 v103, v125, v123
	v_log_f32_e32 v101, v101
	v_max_f32_e32 v103, 0xda24260, v103
	v_mul_f32_e32 v125, 0xbfb8aa3b, v107
	v_exp_f32_e32 v125, v125
	v_mul_f32_e32 v120, 0x3f317217, v101
	v_fma_f32 v120, v101, s95, -v120
	v_fmac_f32_e32 v120, 0x3377d1cf, v101
	v_fmac_f32_e32 v120, 0x3f317217, v101
	v_add_f32_e32 v125, 1.0, v125
	v_rcp_f32_e32 v127, v125
	v_mov_b32_e32 v101, v120
	v_mul_f32_e32 v120, 0xbfb8aa3b, v110
	v_exp_f32_e32 v120, v120
	v_mul_f32_e32 v121, 0x3fb8aa3b, v111
	v_mul_f32_e32 v125, 0x3fb8aa3b, v107
	v_exp_f32_e32 v121, v121
	v_add_f32_e32 v120, 1.0, v120
	v_rcp_f32_e32 v124, v120
	v_mul_f32_e32 v120, 0x3fb8aa3b, v110
	v_exp_f32_e32 v120, v120
	v_exp_f32_e32 v125, v125
	v_fma_f32 v102, v124, v122, v102
	v_max_f32_e32 v102, 0xda24260, v102
	v_add_f32_e32 v120, 1.0, v120
	v_add_f32_e32 v121, 1.0, v121
	v_log_f32_e32 v102, v102
	v_add_f32_e32 v125, 1.0, v125
	v_rcp_f32_e32 v120, v120
	v_rcp_f32_e32 v121, v121
	v_mul_f32_e32 v124, 0x3f317217, v102
	v_fma_f32 v124, v102, s95, -v124
	v_fmac_f32_e32 v124, 0x3377d1cf, v102
	v_fmac_f32_e32 v124, 0x3f317217, v102
	v_rcp_f32_e32 v125, v125
	v_pk_mul_f32 v[118:119], v[116:117], v[118:119]
	v_mov_b32_e32 v102, v124
	v_pk_mul_f32 v[116:117], v[120:121], v[122:123]
	v_log_f32_e32 v103, v103
	s_nop 0
	v_mul_f32_e32 v124, 0x3f317217, v103
	v_fma_f32 v124, v103, s95, -v124
	v_fmac_f32_e32 v124, 0x3377d1cf, v103
	v_fmac_f32_e32 v124, 0x3f317217, v103
	s_nop 1
	v_mov_b32_e32 v103, v124
	v_mul_f32_e32 v124, 0xbfb8aa3b, v106
	v_exp_f32_e32 v124, v124
	s_nop 0
	v_add_f32_e32 v124, 1.0, v124
	v_rcp_f32_e32 v126, v124
	v_mul_f32_e32 v124, 0x3fb8aa3b, v106
	v_exp_f32_e32 v124, v124
	v_fma_f32 v96, v126, v130, v96
	v_max_f32_e32 v96, 0xda24260, v96
	v_add_f32_e32 v124, 1.0, v124
	v_rcp_f32_e32 v124, v124
	v_log_f32_e32 v96, v96
	s_nop 0
	v_mul_f32_e32 v126, 0x3f317217, v96
	v_fma_f32 v126, v96, s95, -v126
	v_fmac_f32_e32 v126, 0x3377d1cf, v96
	v_fmac_f32_e32 v126, 0x3f317217, v96
	s_nop 1
	v_mov_b32_e32 v96, v126
	v_mov_b32_e32 v126, v96
	v_fma_f32 v96, v127, v131, v97
	v_max_f32_e32 v96, 0xda24260, v96
	s_nop 1
	v_log_f32_e32 v96, v96
	s_nop 0
	v_mul_f32_e32 v97, 0x3f317217, v96
	v_fma_f32 v97, v96, s95, -v97
	v_fmac_f32_e32 v97, 0x3377d1cf, v96
	v_fmac_f32_e32 v97, 0x3f317217, v96
	s_nop 1
	v_mov_b32_e32 v96, v97
	v_mov_b32_e32 v127, v96
	v_mul_f32_e32 v96, 0xbfb8aa3b, v114
	v_exp_f32_e32 v96, v96
	v_mul_f32_e32 v97, 0xbfb8aa3b, v115
	v_exp_f32_e32 v97, v97
	v_add_f32_e32 v96, 1.0, v96
	v_rcp_f32_e32 v128, v96
	v_add_f32_e32 v97, 1.0, v97
	v_rcp_f32_e32 v129, v97
	v_mul_f32_e32 v96, 0x3fb8aa3b, v114
	v_fma_f32 v98, v128, v132, v98
	v_max_f32_e32 v98, 0xda24260, v98
	v_fmac_f32_e32 v99, v129, v133
	v_mul_f32_e32 v97, 0x3fb8aa3b, v115
	v_log_f32_e32 v98, v98
	v_exp_f32_e32 v96, v96
	v_exp_f32_e32 v97, v97
	v_mul_f32_e32 v128, 0x3f317217, v98
	v_fma_f32 v128, v98, s95, -v128
	v_fmac_f32_e32 v128, 0x3377d1cf, v98
	v_fmac_f32_e32 v128, 0x3f317217, v98
	v_add_f32_e32 v96, 1.0, v96
	v_add_f32_e32 v97, 1.0, v97
	v_mov_b32_e32 v98, v128
	v_mov_b32_e32 v128, v98
	v_max_f32_e32 v98, 0xda24260, v99
	v_rcp_f32_e32 v96, v96
	v_rcp_f32_e32 v97, v97
	v_log_f32_e32 v98, v98
	v_pk_mul_f32 v[96:97], v[96:97], v[132:133]
	v_mul_f32_e32 v99, 0x3f317217, v98
	v_fma_f32 v99, v98, s95, -v99
	v_fmac_f32_e32 v99, 0x3377d1cf, v98
	v_fmac_f32_e32 v99, 0x3f317217, v98
	s_nop 1
	v_mov_b32_e32 v98, v99
	v_mov_b32_e32 v129, v98
	v_pk_mul_f32 v[98:99], v[124:125], v[130:131]
	global_store_dwordx4 v[112:113], v[100:103], off
	global_store_dwordx4 v[112:113], v[126:129], off offset:16

.LBB0_384:
	s_andn2_b64 vcc, exec, s[36:37]
	s_cbranch_vccnz .LBB0_386
	v_mul_f32_e32 v96, 0xbfb8aa3b, v108
	v_exp_f32_e32 v96, v96
	s_nop 0
	v_add_f32_e32 v96, 1.0, v96
	v_rcp_f32_e32 v118, v96
	v_mul_f32_e32 v96, 0x3fb8aa3b, v108
	v_exp_f32_e32 v96, v96
	s_nop 0
	v_add_f32_e32 v96, 1.0, v96
	v_rcp_f32_e32 v114, v96
	v_mul_f32_e32 v96, 0xbfb8aa3b, v109
	v_exp_f32_e32 v96, v96
	s_nop 0
	v_add_f32_e32 v96, 1.0, v96
	v_rcp_f32_e32 v119, v96
	v_mul_f32_e32 v96, 0x3fb8aa3b, v109
	v_exp_f32_e32 v96, v96
	s_nop 0
	v_add_f32_e32 v96, 1.0, v96
	v_rcp_f32_e32 v115, v96
	global_load_dwordx4 v[96:99], v[148:149], off offset:16
	global_load_dwordx4 v[100:103], v[148:149], off
	s_waitcnt vmcnt(1)
	v_pk_add_f32 v[128:129], v[96:97], 1.0 op_sel_hi:[1,0] neg_lo:[1,0] neg_hi:[1,0]
	s_waitcnt vmcnt(0)
	v_pk_add_f32 v[116:117], v[100:101], 1.0 op_sel_hi:[1,0] neg_lo:[1,0] neg_hi:[1,0]
	v_pk_add_f32 v[120:121], v[102:103], 1.0 op_sel_hi:[1,0] neg_lo:[1,0] neg_hi:[1,0]
	v_fma_f32 v100, v118, v116, v100
	v_max_f32_e32 v100, 0xda24260, v100
	v_fma_f32 v101, v119, v117, v101
	v_max_f32_e32 v101, 0xda24260, v101
	v_log_f32_e32 v100, v100
	v_mul_f32_e32 v119, 0xbfb8aa3b, v111
	v_exp_f32_e32 v119, v119
	v_pk_add_f32 v[130:131], v[98:99], 1.0 op_sel_hi:[1,0] neg_lo:[1,0] neg_hi:[1,0]
	v_mul_f32_e32 v118, 0x3f317217, v100
	v_fma_f32 v118, v100, s95, -v118
	v_fmac_f32_e32 v118, 0x3377d1cf, v100
	v_fmac_f32_e32 v118, 0x3f317217, v100
	v_add_f32_e32 v119, 1.0, v119
	v_rcp_f32_e32 v123, v119
	v_mov_b32_e32 v100, v118
	v_fmac_f32_e32 v103, v123, v121
	v_log_f32_e32 v101, v101
	v_max_f32_e32 v103, 0xda24260, v103
	v_mul_f32_e32 v123, 0xbfb8aa3b, v107
	v_exp_f32_e32 v123, v123
	v_mul_f32_e32 v118, 0x3f317217, v101
	v_fma_f32 v118, v101, s95, -v118
	v_fmac_f32_e32 v118, 0x3377d1cf, v101
	v_fmac_f32_e32 v118, 0x3f317217, v101
	v_add_f32_e32 v123, 1.0, v123
	v_rcp_f32_e32 v125, v123
	v_mov_b32_e32 v101, v118
	v_mul_f32_e32 v118, 0xbfb8aa3b, v110
	v_exp_f32_e32 v118, v118
	v_mul_f32_e32 v119, 0x3fb8aa3b, v111
	v_mul_f32_e32 v123, 0x3fb8aa3b, v107
	v_exp_f32_e32 v119, v119
	v_add_f32_e32 v118, 1.0, v118
	v_rcp_f32_e32 v122, v118
	v_mul_f32_e32 v118, 0x3fb8aa3b, v110
	v_exp_f32_e32 v118, v118
	v_exp_f32_e32 v123, v123
	v_fma_f32 v102, v122, v120, v102
	v_max_f32_e32 v102, 0xda24260, v102
	v_add_f32_e32 v118, 1.0, v118
	v_add_f32_e32 v119, 1.0, v119
	v_log_f32_e32 v102, v102
	v_add_f32_e32 v123, 1.0, v123
	v_rcp_f32_e32 v118, v118
	v_rcp_f32_e32 v119, v119
	v_mul_f32_e32 v122, 0x3f317217, v102
	v_fma_f32 v122, v102, s95, -v122
	v_fmac_f32_e32 v122, 0x3377d1cf, v102
	v_fmac_f32_e32 v122, 0x3f317217, v102
	v_rcp_f32_e32 v123, v123
	v_pk_mul_f32 v[116:117], v[114:115], v[116:117]
	v_mov_b32_e32 v102, v122
	v_pk_mul_f32 v[114:115], v[118:119], v[120:121]
	v_log_f32_e32 v103, v103
	v_lshl_add_u64 v[118:119], v[146:147], 0, v[104:105]
	v_mul_f32_e32 v122, 0x3f317217, v103
	v_fma_f32 v122, v103, s95, -v122
	v_fmac_f32_e32 v122, 0x3377d1cf, v103
	v_fmac_f32_e32 v122, 0x3f317217, v103
	s_nop 1
	v_mov_b32_e32 v103, v122
	v_mul_f32_e32 v122, 0xbfb8aa3b, v106
	v_exp_f32_e32 v122, v122
	s_nop 0
	v_add_f32_e32 v122, 1.0, v122
	v_rcp_f32_e32 v124, v122
	v_mul_f32_e32 v122, 0x3fb8aa3b, v106
	v_exp_f32_e32 v122, v122
	v_fma_f32 v96, v124, v128, v96
	v_max_f32_e32 v96, 0xda24260, v96
	v_add_f32_e32 v122, 1.0, v122
	v_rcp_f32_e32 v122, v122
	v_log_f32_e32 v96, v96
	s_nop 0
	v_mul_f32_e32 v124, 0x3f317217, v96
	v_fma_f32 v124, v96, s95, -v124
	v_fmac_f32_e32 v124, 0x3377d1cf, v96
	v_fmac_f32_e32 v124, 0x3f317217, v96
	s_nop 1
	v_mov_b32_e32 v96, v124
	v_mov_b32_e32 v124, v96
	v_fma_f32 v96, v125, v129, v97
	v_max_f32_e32 v96, 0xda24260, v96
	s_nop 1
	v_log_f32_e32 v96, v96
	s_nop 0
	v_mul_f32_e32 v97, 0x3f317217, v96
	v_fma_f32 v97, v96, s95, -v97
	v_fmac_f32_e32 v97, 0x3377d1cf, v96
	v_fmac_f32_e32 v97, 0x3f317217, v96
	s_nop 1
	v_mov_b32_e32 v96, v97
	v_mov_b32_e32 v125, v96
	v_mul_f32_e32 v96, 0xbfb8aa3b, v112
	v_exp_f32_e32 v96, v96
	v_mul_f32_e32 v97, 0xbfb8aa3b, v113
	v_exp_f32_e32 v97, v97
	v_add_f32_e32 v96, 1.0, v96
	v_rcp_f32_e32 v126, v96
	v_add_f32_e32 v97, 1.0, v97
	v_rcp_f32_e32 v127, v97
	v_mul_f32_e32 v96, 0x3fb8aa3b, v112
	v_fma_f32 v98, v126, v130, v98
	v_max_f32_e32 v98, 0xda24260, v98
	v_fmac_f32_e32 v99, v127, v131
	v_mul_f32_e32 v97, 0x3fb8aa3b, v113
	v_log_f32_e32 v98, v98
	v_exp_f32_e32 v96, v96
	v_exp_f32_e32 v97, v97
	v_mul_f32_e32 v126, 0x3f317217, v98
	v_fma_f32 v126, v98, s95, -v126
	v_fmac_f32_e32 v126, 0x3377d1cf, v98
	v_fmac_f32_e32 v126, 0x3f317217, v98
	v_add_f32_e32 v96, 1.0, v96
	v_add_f32_e32 v97, 1.0, v97
	v_mov_b32_e32 v98, v126
	v_mov_b32_e32 v126, v98
	v_max_f32_e32 v98, 0xda24260, v99
	v_rcp_f32_e32 v96, v96
	v_rcp_f32_e32 v97, v97
	v_log_f32_e32 v98, v98
	v_pk_mul_f32 v[96:97], v[96:97], v[130:131]
	v_mul_f32_e32 v99, 0x3f317217, v98
	v_fma_f32 v99, v98, s95, -v99
	v_fmac_f32_e32 v99, 0x3377d1cf, v98
	v_fmac_f32_e32 v99, 0x3f317217, v98
	s_nop 1
	v_mov_b32_e32 v98, v99
	v_mov_b32_e32 v127, v98
	v_pk_mul_f32 v[98:99], v[122:123], v[128:129]
	global_store_dwordx4 v[118:119], v[100:103], off
	global_store_dwordx4 v[118:119], v[124:127], off offset:16

.LBB0_396:
	s_andn2_b64 vcc, exec, s[36:37]
	s_cbranch_vccnz .LBB0_398
	global_load_dwordx4 v[88:91], v[148:149], off offset:528
	global_load_dwordx4 v[92:95], v[148:149], off offset:512
	v_mul_f32_e32 v108, 0xbfb8aa3b, v100
	v_exp_f32_e32 v108, v108
	v_mul_f32_e32 v109, 0xbfb8aa3b, v101
	v_exp_f32_e32 v109, v109
	v_lshl_add_u64 v[104:105], v[150:151], 0, v[104:105]
	v_add_f32_e32 v108, 1.0, v108
	v_rcp_f32_e32 v112, v108
	v_add_f32_e32 v109, 1.0, v109
	v_rcp_f32_e32 v113, v109
	v_mul_f32_e32 v108, 0x3fb8aa3b, v100
	v_mul_f32_e32 v109, 0x3fb8aa3b, v101
	v_exp_f32_e32 v108, v108
	v_exp_f32_e32 v109, v109
	v_add_f32_e32 v108, 1.0, v108
	v_add_f32_e32 v109, 1.0, v109
	v_rcp_f32_e32 v108, v108
	v_rcp_f32_e32 v109, v109
	s_waitcnt vmcnt(1)
	v_pk_add_f32 v[122:123], v[88:89], 1.0 op_sel_hi:[1,0] neg_lo:[1,0] neg_hi:[1,0]
	s_waitcnt vmcnt(0)
	v_pk_add_f32 v[110:111], v[92:93], 1.0 op_sel_hi:[1,0] neg_lo:[1,0] neg_hi:[1,0]
	v_pk_add_f32 v[114:115], v[94:95], 1.0 op_sel_hi:[1,0] neg_lo:[1,0] neg_hi:[1,0]
	v_fma_f32 v92, v112, v110, v92
	v_max_f32_e32 v92, 0xda24260, v92
	v_fma_f32 v93, v113, v111, v93
	v_max_f32_e32 v93, 0xda24260, v93
	v_log_f32_e32 v92, v92
	v_mul_f32_e32 v113, 0xbfb8aa3b, v103
	v_exp_f32_e32 v113, v113
	v_pk_add_f32 v[124:125], v[90:91], 1.0 op_sel_hi:[1,0] neg_lo:[1,0] neg_hi:[1,0]
	v_mul_f32_e32 v112, 0x3f317217, v92
	v_fma_f32 v112, v92, s95, -v112
	v_fmac_f32_e32 v112, 0x3377d1cf, v92
	v_fmac_f32_e32 v112, 0x3f317217, v92
	v_add_f32_e32 v113, 1.0, v113
	v_rcp_f32_e32 v117, v113
	v_mov_b32_e32 v92, v112
	v_fmac_f32_e32 v95, v117, v115
	v_log_f32_e32 v93, v93
	v_max_f32_e32 v95, 0xda24260, v95
	v_mul_f32_e32 v117, 0xbfb8aa3b, v99
	v_exp_f32_e32 v117, v117
	v_mul_f32_e32 v112, 0x3f317217, v93
	v_fma_f32 v112, v93, s95, -v112
	v_fmac_f32_e32 v112, 0x3377d1cf, v93
	v_fmac_f32_e32 v112, 0x3f317217, v93
	v_add_f32_e32 v117, 1.0, v117
	v_rcp_f32_e32 v119, v117
	v_mov_b32_e32 v93, v112
	v_mul_f32_e32 v112, 0xbfb8aa3b, v102
	v_exp_f32_e32 v112, v112
	v_mul_f32_e32 v113, 0x3fb8aa3b, v103
	v_mul_f32_e32 v117, 0x3fb8aa3b, v99
	v_exp_f32_e32 v113, v113
	v_add_f32_e32 v112, 1.0, v112
	v_rcp_f32_e32 v116, v112
	v_mul_f32_e32 v112, 0x3fb8aa3b, v102
	v_exp_f32_e32 v112, v112
	v_exp_f32_e32 v117, v117
	v_fma_f32 v94, v116, v114, v94
	v_max_f32_e32 v94, 0xda24260, v94
	v_add_f32_e32 v112, 1.0, v112
	v_add_f32_e32 v113, 1.0, v113
	v_log_f32_e32 v94, v94
	v_add_f32_e32 v117, 1.0, v117
	v_rcp_f32_e32 v112, v112
	v_rcp_f32_e32 v113, v113
	v_mul_f32_e32 v116, 0x3f317217, v94
	v_fma_f32 v116, v94, s95, -v116
	v_fmac_f32_e32 v116, 0x3377d1cf, v94
	v_fmac_f32_e32 v116, 0x3f317217, v94
	v_rcp_f32_e32 v117, v117
	v_pk_mul_f32 v[110:111], v[108:109], v[110:111]
	v_mov_b32_e32 v94, v116
	v_pk_mul_f32 v[108:109], v[112:113], v[114:115]
	v_log_f32_e32 v95, v95
	s_nop 0
	v_mul_f32_e32 v116, 0x3f317217, v95
	v_fma_f32 v116, v95, s95, -v116
	v_fmac_f32_e32 v116, 0x3377d1cf, v95
	v_fmac_f32_e32 v116, 0x3f317217, v95
	s_nop 1
	v_mov_b32_e32 v95, v116
	v_mul_f32_e32 v116, 0xbfb8aa3b, v98
	v_exp_f32_e32 v116, v116
	s_nop 0
	v_add_f32_e32 v116, 1.0, v116
	v_rcp_f32_e32 v118, v116
	v_mul_f32_e32 v116, 0x3fb8aa3b, v98
	v_exp_f32_e32 v116, v116
	v_fma_f32 v88, v118, v122, v88
	v_max_f32_e32 v88, 0xda24260, v88
	v_add_f32_e32 v116, 1.0, v116
	v_rcp_f32_e32 v116, v116
	v_log_f32_e32 v88, v88
	s_nop 0
	v_mul_f32_e32 v118, 0x3f317217, v88
	v_fma_f32 v118, v88, s95, -v118
	v_fmac_f32_e32 v118, 0x3377d1cf, v88
	v_fmac_f32_e32 v118, 0x3f317217, v88
	s_nop 1
	v_mov_b32_e32 v88, v118
	v_mov_b32_e32 v118, v88
	v_fma_f32 v88, v119, v123, v89
	v_max_f32_e32 v88, 0xda24260, v88
	s_nop 1
	v_log_f32_e32 v88, v88
	s_nop 0
	v_mul_f32_e32 v89, 0x3f317217, v88
	v_fma_f32 v89, v88, s95, -v89
	v_fmac_f32_e32 v89, 0x3377d1cf, v88
	v_fmac_f32_e32 v89, 0x3f317217, v88
	s_nop 1
	v_mov_b32_e32 v88, v89
	v_mov_b32_e32 v119, v88
	v_mul_f32_e32 v88, 0xbfb8aa3b, v106
	v_exp_f32_e32 v88, v88
	v_mul_f32_e32 v89, 0xbfb8aa3b, v107
	v_exp_f32_e32 v89, v89
	v_add_f32_e32 v88, 1.0, v88
	v_rcp_f32_e32 v120, v88
	v_add_f32_e32 v89, 1.0, v89
	v_rcp_f32_e32 v121, v89
	v_mul_f32_e32 v88, 0x3fb8aa3b, v106
	v_fma_f32 v90, v120, v124, v90
	v_max_f32_e32 v90, 0xda24260, v90
	v_fmac_f32_e32 v91, v121, v125
	v_mul_f32_e32 v89, 0x3fb8aa3b, v107
	v_log_f32_e32 v90, v90
	v_exp_f32_e32 v88, v88
	v_exp_f32_e32 v89, v89
	v_mul_f32_e32 v120, 0x3f317217, v90
	v_fma_f32 v120, v90, s95, -v120
	v_fmac_f32_e32 v120, 0x3377d1cf, v90
	v_fmac_f32_e32 v120, 0x3f317217, v90
	v_add_f32_e32 v88, 1.0, v88
	v_add_f32_e32 v89, 1.0, v89
	v_mov_b32_e32 v90, v120
	v_mov_b32_e32 v120, v90
	v_max_f32_e32 v90, 0xda24260, v91
	v_rcp_f32_e32 v88, v88
	v_rcp_f32_e32 v89, v89
	v_log_f32_e32 v90, v90
	v_pk_mul_f32 v[88:89], v[88:89], v[124:125]
	v_mul_f32_e32 v91, 0x3f317217, v90
	v_fma_f32 v91, v90, s95, -v91
	v_fmac_f32_e32 v91, 0x3377d1cf, v90
	v_fmac_f32_e32 v91, 0x3f317217, v90
	s_nop 1
	v_mov_b32_e32 v90, v91
	v_mov_b32_e32 v121, v90
	v_pk_mul_f32 v[90:91], v[116:117], v[122:123]
	global_store_dwordx4 v[104:105], v[92:95], off
	global_store_dwordx4 v[104:105], v[118:121], off offset:16

.LBB0_408:
	s_andn2_b64 vcc, exec, s[36:37]
	s_cbranch_vccnz .LBB0_410
	v_mul_f32_e32 v88, 0xbfb8aa3b, v102
	v_exp_f32_e32 v88, v88
	v_mul_f32_e32 v113, 0xbfb8aa3b, v105
	v_exp_f32_e32 v113, v113
	v_mul_f32_e32 v117, 0xbfb8aa3b, v101
	v_add_f32_e32 v88, 1.0, v88
	v_rcp_f32_e32 v99, v88
	v_mul_f32_e32 v88, 0x3fb8aa3b, v102
	v_exp_f32_e32 v88, v88
	v_add_f32_e32 v113, 1.0, v113
	v_rcp_f32_e32 v116, v113
	v_exp_f32_e32 v117, v117
	v_add_f32_e32 v88, 1.0, v88
	v_rcp_f32_e32 v108, v88
	v_mul_f32_e32 v88, 0xbfb8aa3b, v103
	v_exp_f32_e32 v88, v88
	v_add_f32_e32 v117, 1.0, v117
	v_rcp_f32_e32 v119, v117
	v_mul_f32_e32 v113, 0x3fb8aa3b, v105
	v_add_f32_e32 v88, 1.0, v88
	v_rcp_f32_e32 v112, v88
	v_mul_f32_e32 v88, 0x3fb8aa3b, v103
	v_exp_f32_e32 v88, v88
	v_mul_f32_e32 v117, 0x3fb8aa3b, v101
	v_exp_f32_e32 v113, v113
	v_exp_f32_e32 v117, v117
	v_add_f32_e32 v88, 1.0, v88
	v_rcp_f32_e32 v109, v88
	global_load_dwordx4 v[88:91], v[148:149], off offset:16
	global_load_dwordx4 v[92:95], v[148:149], off
	v_add_f32_e32 v113, 1.0, v113
	v_add_f32_e32 v117, 1.0, v117
	v_rcp_f32_e32 v113, v113
	v_rcp_f32_e32 v117, v117
	s_waitcnt vmcnt(1)
	v_pk_add_f32 v[122:123], v[88:89], 1.0 op_sel_hi:[1,0] neg_lo:[1,0] neg_hi:[1,0]
	s_waitcnt vmcnt(0)
	v_pk_add_f32 v[110:111], v[92:93], 1.0 op_sel_hi:[1,0] neg_lo:[1,0] neg_hi:[1,0]
	v_pk_add_f32 v[114:115], v[94:95], 1.0 op_sel_hi:[1,0] neg_lo:[1,0] neg_hi:[1,0]
	v_fma_f32 v92, v99, v110, v92
	v_max_f32_e32 v92, 0xda24260, v92
	v_fma_f32 v93, v112, v111, v93
	v_max_f32_e32 v93, 0xda24260, v93
	v_log_f32_e32 v92, v92
	v_fmac_f32_e32 v95, v116, v115
	v_max_f32_e32 v95, 0xda24260, v95
	v_pk_add_f32 v[124:125], v[90:91], 1.0 op_sel_hi:[1,0] neg_lo:[1,0] neg_hi:[1,0]
	v_mul_f32_e32 v99, 0x3f317217, v92
	v_fma_f32 v99, v92, s95, -v99
	v_fmac_f32_e32 v99, 0x3377d1cf, v92
	v_fmac_f32_e32 v99, 0x3f317217, v92
	v_mul_f32_e32 v112, 0x3fb8aa3b, v104
	v_mul_f32_e32 v116, 0x3fb8aa3b, v100
	v_mov_b32_e32 v92, v99
	v_exp_f32_e32 v112, v112
	v_log_f32_e32 v93, v93
	v_exp_f32_e32 v116, v116
	v_add_f32_e32 v112, 1.0, v112
	v_rcp_f32_e32 v112, v112
	v_mul_f32_e32 v99, 0x3f317217, v93
	v_fma_f32 v99, v93, s95, -v99
	v_fmac_f32_e32 v99, 0x3377d1cf, v93
	v_fmac_f32_e32 v99, 0x3f317217, v93
	v_add_f32_e32 v116, 1.0, v116
	v_rcp_f32_e32 v116, v116
	v_mov_b32_e32 v93, v99
	v_mul_f32_e32 v99, 0xbfb8aa3b, v104
	v_exp_f32_e32 v99, v99
	v_pk_mul_f32 v[110:111], v[108:109], v[110:111]
	v_pk_mul_f32 v[108:109], v[112:113], v[114:115]
	v_lshl_add_u64 v[112:113], v[146:147], 0, v[96:97]
	v_add_f32_e32 v99, 1.0, v99
	v_rcp_f32_e32 v99, v99
	s_nop 0
	v_fma_f32 v94, v99, v114, v94
	v_max_f32_e32 v94, 0xda24260, v94
	s_nop 1
	v_log_f32_e32 v94, v94
	s_nop 0
	v_mul_f32_e32 v99, 0x3f317217, v94
	v_fma_f32 v99, v94, s95, -v99
	v_fmac_f32_e32 v99, 0x3377d1cf, v94
	v_fmac_f32_e32 v99, 0x3f317217, v94
	s_nop 1
	v_mov_b32_e32 v94, v99
	s_nop 0
	v_log_f32_e32 v95, v95
	s_nop 0
	v_mul_f32_e32 v99, 0x3f317217, v95
	v_fma_f32 v99, v95, s95, -v99
	v_fmac_f32_e32 v99, 0x3377d1cf, v95
	v_fmac_f32_e32 v99, 0x3f317217, v95
	s_nop 1
	v_mov_b32_e32 v95, v99
	v_mul_f32_e32 v99, 0xbfb8aa3b, v100
	v_exp_f32_e32 v99, v99
	s_nop 0
	v_add_f32_e32 v99, 1.0, v99
	v_rcp_f32_e32 v99, v99
	s_nop 0
	v_fma_f32 v88, v99, v122, v88
	v_max_f32_e32 v88, 0xda24260, v88
	s_nop 1
	v_log_f32_e32 v88, v88
	s_nop 0
	v_mul_f32_e32 v99, 0x3f317217, v88
	v_fma_f32 v99, v88, s95, -v99
	v_fmac_f32_e32 v99, 0x3377d1cf, v88
	v_fmac_f32_e32 v99, 0x3f317217, v88
	s_nop 1
	v_mov_b32_e32 v88, v99
	v_mov_b32_e32 v118, v88
	v_fma_f32 v88, v119, v123, v89
	v_max_f32_e32 v88, 0xda24260, v88
	s_nop 1
	v_log_f32_e32 v88, v88
	s_nop 0
	v_mul_f32_e32 v89, 0x3f317217, v88
	v_fma_f32 v89, v88, s95, -v89
	v_fmac_f32_e32 v89, 0x3377d1cf, v88
	v_fmac_f32_e32 v89, 0x3f317217, v88
	s_nop 1
	v_mov_b32_e32 v88, v89
	v_mov_b32_e32 v119, v88
	v_mul_f32_e32 v88, 0xbfb8aa3b, v106
	v_exp_f32_e32 v88, v88
	v_mul_f32_e32 v89, 0xbfb8aa3b, v107
	v_exp_f32_e32 v89, v89
	v_add_f32_e32 v88, 1.0, v88
	v_rcp_f32_e32 v99, v88
	v_add_f32_e32 v89, 1.0, v89
	v_rcp_f32_e32 v121, v89
	v_mul_f32_e32 v88, 0x3fb8aa3b, v106
	v_fma_f32 v90, v99, v124, v90
	v_max_f32_e32 v90, 0xda24260, v90
	v_fmac_f32_e32 v91, v121, v125
	v_mul_f32_e32 v89, 0x3fb8aa3b, v107
	v_log_f32_e32 v90, v90
	v_exp_f32_e32 v88, v88
	v_exp_f32_e32 v89, v89
	v_mul_f32_e32 v99, 0x3f317217, v90
	v_fma_f32 v99, v90, s95, -v99
	v_fmac_f32_e32 v99, 0x3377d1cf, v90
	v_fmac_f32_e32 v99, 0x3f317217, v90
	v_add_f32_e32 v88, 1.0, v88
	v_add_f32_e32 v89, 1.0, v89
	v_mov_b32_e32 v90, v99
	v_mov_b32_e32 v120, v90
	v_max_f32_e32 v90, 0xda24260, v91
	v_rcp_f32_e32 v88, v88
	v_rcp_f32_e32 v89, v89
	v_log_f32_e32 v90, v90
	v_pk_mul_f32 v[88:89], v[88:89], v[124:125]
	v_mul_f32_e32 v91, 0x3f317217, v90
	v_fma_f32 v91, v90, s95, -v91
	v_fmac_f32_e32 v91, 0x3377d1cf, v90
	v_fmac_f32_e32 v91, 0x3f317217, v90
	s_nop 1
	v_mov_b32_e32 v90, v91
	v_mov_b32_e32 v121, v90
	v_pk_mul_f32 v[90:91], v[116:117], v[122:123]
	global_store_dwordx4 v[112:113], v[92:95], off
	global_store_dwordx4 v[112:113], v[118:121], off offset:16

.LBB0_420:
	s_andn2_b64 vcc, exec, s[36:37]
	s_cbranch_vccnz .LBB0_422
	global_load_dwordx4 v[80:83], v[148:149], off offset:528
	global_load_dwordx4 v[84:87], v[148:149], off offset:512
	v_mul_f32_e32 v100, 0xbfb8aa3b, v92
	v_exp_f32_e32 v100, v100
	v_mul_f32_e32 v101, 0xbfb8aa3b, v93
	v_exp_f32_e32 v101, v101
	v_lshl_add_u64 v[96:97], v[150:151], 0, v[96:97]
	v_add_f32_e32 v100, 1.0, v100
	v_rcp_f32_e32 v104, v100
	v_add_f32_e32 v101, 1.0, v101
	v_rcp_f32_e32 v105, v101
	v_mul_f32_e32 v100, 0x3fb8aa3b, v92
	v_mul_f32_e32 v101, 0x3fb8aa3b, v93
	v_exp_f32_e32 v100, v100
	v_exp_f32_e32 v101, v101
	v_add_f32_e32 v100, 1.0, v100
	v_add_f32_e32 v101, 1.0, v101
	v_rcp_f32_e32 v100, v100
	v_rcp_f32_e32 v101, v101
	s_waitcnt vmcnt(1)
	v_pk_add_f32 v[114:115], v[80:81], 1.0 op_sel_hi:[1,0] neg_lo:[1,0] neg_hi:[1,0]
	s_waitcnt vmcnt(0)
	v_pk_add_f32 v[102:103], v[84:85], 1.0 op_sel_hi:[1,0] neg_lo:[1,0] neg_hi:[1,0]
	v_pk_add_f32 v[106:107], v[86:87], 1.0 op_sel_hi:[1,0] neg_lo:[1,0] neg_hi:[1,0]
	v_fma_f32 v84, v104, v102, v84
	v_max_f32_e32 v84, 0xda24260, v84
	v_fma_f32 v85, v105, v103, v85
	v_max_f32_e32 v85, 0xda24260, v85
	v_log_f32_e32 v84, v84
	v_mul_f32_e32 v105, 0xbfb8aa3b, v95
	v_exp_f32_e32 v105, v105
	v_pk_add_f32 v[116:117], v[82:83], 1.0 op_sel_hi:[1,0] neg_lo:[1,0] neg_hi:[1,0]
	v_mul_f32_e32 v104, 0x3f317217, v84
	v_fma_f32 v104, v84, s95, -v104
	v_fmac_f32_e32 v104, 0x3377d1cf, v84
	v_fmac_f32_e32 v104, 0x3f317217, v84
	v_add_f32_e32 v105, 1.0, v105
	v_rcp_f32_e32 v109, v105
	v_mov_b32_e32 v84, v104
	v_fmac_f32_e32 v87, v109, v107
	v_log_f32_e32 v85, v85
	v_max_f32_e32 v87, 0xda24260, v87
	v_mul_f32_e32 v109, 0xbfb8aa3b, v91
	v_exp_f32_e32 v109, v109
	v_mul_f32_e32 v104, 0x3f317217, v85
	v_fma_f32 v104, v85, s95, -v104
	v_fmac_f32_e32 v104, 0x3377d1cf, v85
	v_fmac_f32_e32 v104, 0x3f317217, v85
	v_add_f32_e32 v109, 1.0, v109
	v_rcp_f32_e32 v111, v109
	v_mov_b32_e32 v85, v104
	v_mul_f32_e32 v104, 0xbfb8aa3b, v94
	v_exp_f32_e32 v104, v104
	v_mul_f32_e32 v105, 0x3fb8aa3b, v95
	v_mul_f32_e32 v109, 0x3fb8aa3b, v91
	v_exp_f32_e32 v105, v105
	v_add_f32_e32 v104, 1.0, v104
	v_rcp_f32_e32 v108, v104
	v_mul_f32_e32 v104, 0x3fb8aa3b, v94
	v_exp_f32_e32 v104, v104
	v_exp_f32_e32 v109, v109
	v_fma_f32 v86, v108, v106, v86
	v_max_f32_e32 v86, 0xda24260, v86
	v_add_f32_e32 v104, 1.0, v104
	v_add_f32_e32 v105, 1.0, v105
	v_log_f32_e32 v86, v86
	v_add_f32_e32 v109, 1.0, v109
	v_rcp_f32_e32 v104, v104
	v_rcp_f32_e32 v105, v105
	v_mul_f32_e32 v108, 0x3f317217, v86
	v_fma_f32 v108, v86, s95, -v108
	v_fmac_f32_e32 v108, 0x3377d1cf, v86
	v_fmac_f32_e32 v108, 0x3f317217, v86
	v_rcp_f32_e32 v109, v109
	v_pk_mul_f32 v[102:103], v[100:101], v[102:103]
	v_mov_b32_e32 v86, v108
	v_pk_mul_f32 v[100:101], v[104:105], v[106:107]
	v_log_f32_e32 v87, v87
	s_nop 0
	v_mul_f32_e32 v108, 0x3f317217, v87
	v_fma_f32 v108, v87, s95, -v108
	v_fmac_f32_e32 v108, 0x3377d1cf, v87
	v_fmac_f32_e32 v108, 0x3f317217, v87
	s_nop 1
	v_mov_b32_e32 v87, v108
	v_mul_f32_e32 v108, 0xbfb8aa3b, v90
	v_exp_f32_e32 v108, v108
	s_nop 0
	v_add_f32_e32 v108, 1.0, v108
	v_rcp_f32_e32 v110, v108
	v_mul_f32_e32 v108, 0x3fb8aa3b, v90
	v_exp_f32_e32 v108, v108
	v_fma_f32 v80, v110, v114, v80
	v_max_f32_e32 v80, 0xda24260, v80
	v_add_f32_e32 v108, 1.0, v108
	v_rcp_f32_e32 v108, v108
	v_log_f32_e32 v80, v80
	s_nop 0
	v_mul_f32_e32 v110, 0x3f317217, v80
	v_fma_f32 v110, v80, s95, -v110
	v_fmac_f32_e32 v110, 0x3377d1cf, v80
	v_fmac_f32_e32 v110, 0x3f317217, v80
	s_nop 1
	v_mov_b32_e32 v80, v110
	v_mov_b32_e32 v110, v80
	v_fma_f32 v80, v111, v115, v81
	v_max_f32_e32 v80, 0xda24260, v80
	s_nop 1
	v_log_f32_e32 v80, v80
	s_nop 0
	v_mul_f32_e32 v81, 0x3f317217, v80
	v_fma_f32 v81, v80, s95, -v81
	v_fmac_f32_e32 v81, 0x3377d1cf, v80
	v_fmac_f32_e32 v81, 0x3f317217, v80
	s_nop 1
	v_mov_b32_e32 v80, v81
	v_mov_b32_e32 v111, v80
	v_mul_f32_e32 v80, 0xbfb8aa3b, v98
	v_exp_f32_e32 v80, v80
	v_mul_f32_e32 v81, 0xbfb8aa3b, v99
	v_exp_f32_e32 v81, v81
	v_add_f32_e32 v80, 1.0, v80
	v_rcp_f32_e32 v112, v80
	v_add_f32_e32 v81, 1.0, v81
	v_rcp_f32_e32 v113, v81
	v_mul_f32_e32 v80, 0x3fb8aa3b, v98
	v_fma_f32 v82, v112, v116, v82
	v_max_f32_e32 v82, 0xda24260, v82
	v_fmac_f32_e32 v83, v113, v117
	v_mul_f32_e32 v81, 0x3fb8aa3b, v99
	v_log_f32_e32 v82, v82
	v_exp_f32_e32 v80, v80
	v_exp_f32_e32 v81, v81
	v_mul_f32_e32 v112, 0x3f317217, v82
	v_fma_f32 v112, v82, s95, -v112
	v_fmac_f32_e32 v112, 0x3377d1cf, v82
	v_fmac_f32_e32 v112, 0x3f317217, v82
	v_add_f32_e32 v80, 1.0, v80
	v_add_f32_e32 v81, 1.0, v81
	v_mov_b32_e32 v82, v112
	v_mov_b32_e32 v112, v82
	v_max_f32_e32 v82, 0xda24260, v83
	v_rcp_f32_e32 v80, v80
	v_rcp_f32_e32 v81, v81
	v_log_f32_e32 v82, v82
	v_pk_mul_f32 v[80:81], v[80:81], v[116:117]
	v_mul_f32_e32 v83, 0x3f317217, v82
	v_fma_f32 v83, v82, s95, -v83
	v_fmac_f32_e32 v83, 0x3377d1cf, v82
	v_fmac_f32_e32 v83, 0x3f317217, v82
	s_nop 1
	v_mov_b32_e32 v82, v83
	v_mov_b32_e32 v113, v82
	v_pk_mul_f32 v[82:83], v[108:109], v[114:115]
	global_store_dwordx4 v[96:97], v[84:87], off
	global_store_dwordx4 v[96:97], v[110:113], off offset:16

.LBB0_432:
	s_andn2_b64 vcc, exec, s[36:37]
	s_cbranch_vccnz .LBB0_434
	v_mul_f32_e32 v80, 0xbfb8aa3b, v94
	v_exp_f32_e32 v80, v80
	v_mul_f32_e32 v105, 0xbfb8aa3b, v97
	v_exp_f32_e32 v105, v105
	v_mul_f32_e32 v109, 0xbfb8aa3b, v93
	v_add_f32_e32 v80, 1.0, v80
	v_rcp_f32_e32 v91, v80
	v_mul_f32_e32 v80, 0x3fb8aa3b, v94
	v_exp_f32_e32 v80, v80
	v_add_f32_e32 v105, 1.0, v105
	v_rcp_f32_e32 v108, v105
	v_exp_f32_e32 v109, v109
	v_add_f32_e32 v80, 1.0, v80
	v_rcp_f32_e32 v100, v80
	v_mul_f32_e32 v80, 0xbfb8aa3b, v95
	v_exp_f32_e32 v80, v80
	v_add_f32_e32 v109, 1.0, v109
	v_rcp_f32_e32 v111, v109
	v_mul_f32_e32 v105, 0x3fb8aa3b, v97
	v_add_f32_e32 v80, 1.0, v80
	v_rcp_f32_e32 v104, v80
	v_mul_f32_e32 v80, 0x3fb8aa3b, v95
	v_exp_f32_e32 v80, v80
	v_mul_f32_e32 v109, 0x3fb8aa3b, v93
	v_exp_f32_e32 v105, v105
	v_exp_f32_e32 v109, v109
	v_add_f32_e32 v80, 1.0, v80
	v_rcp_f32_e32 v101, v80
	global_load_dwordx4 v[80:83], v[148:149], off offset:16
	global_load_dwordx4 v[84:87], v[148:149], off
	v_add_f32_e32 v105, 1.0, v105
	v_add_f32_e32 v109, 1.0, v109
	v_rcp_f32_e32 v105, v105
	v_rcp_f32_e32 v109, v109
	s_waitcnt vmcnt(1)
	v_pk_add_f32 v[114:115], v[80:81], 1.0 op_sel_hi:[1,0] neg_lo:[1,0] neg_hi:[1,0]
	s_waitcnt vmcnt(0)
	v_pk_add_f32 v[102:103], v[84:85], 1.0 op_sel_hi:[1,0] neg_lo:[1,0] neg_hi:[1,0]
	v_pk_add_f32 v[106:107], v[86:87], 1.0 op_sel_hi:[1,0] neg_lo:[1,0] neg_hi:[1,0]
	v_fma_f32 v84, v91, v102, v84
	v_max_f32_e32 v84, 0xda24260, v84
	v_fma_f32 v85, v104, v103, v85
	v_max_f32_e32 v85, 0xda24260, v85
	v_log_f32_e32 v84, v84
	v_fmac_f32_e32 v87, v108, v107
	v_max_f32_e32 v87, 0xda24260, v87
	v_pk_add_f32 v[116:117], v[82:83], 1.0 op_sel_hi:[1,0] neg_lo:[1,0] neg_hi:[1,0]
	v_mul_f32_e32 v91, 0x3f317217, v84
	v_fma_f32 v91, v84, s95, -v91
	v_fmac_f32_e32 v91, 0x3377d1cf, v84
	v_fmac_f32_e32 v91, 0x3f317217, v84
	v_mul_f32_e32 v104, 0x3fb8aa3b, v96
	v_mul_f32_e32 v108, 0x3fb8aa3b, v92
	v_mov_b32_e32 v84, v91
	v_exp_f32_e32 v104, v104
	v_log_f32_e32 v85, v85
	v_exp_f32_e32 v108, v108
	v_add_f32_e32 v104, 1.0, v104
	v_rcp_f32_e32 v104, v104
	v_mul_f32_e32 v91, 0x3f317217, v85
	v_fma_f32 v91, v85, s95, -v91
	v_fmac_f32_e32 v91, 0x3377d1cf, v85
	v_fmac_f32_e32 v91, 0x3f317217, v85
	v_add_f32_e32 v108, 1.0, v108
	v_rcp_f32_e32 v108, v108
	v_mov_b32_e32 v85, v91
	v_mul_f32_e32 v91, 0xbfb8aa3b, v96
	v_exp_f32_e32 v91, v91
	v_pk_mul_f32 v[102:103], v[100:101], v[102:103]
	v_pk_mul_f32 v[100:101], v[104:105], v[106:107]
	v_lshl_add_u64 v[104:105], v[146:147], 0, v[88:89]
	v_add_f32_e32 v91, 1.0, v91
	v_rcp_f32_e32 v91, v91
	s_nop 0
	v_fma_f32 v86, v91, v106, v86
	v_max_f32_e32 v86, 0xda24260, v86
	s_nop 1
	v_log_f32_e32 v86, v86
	s_nop 0
	v_mul_f32_e32 v91, 0x3f317217, v86
	v_fma_f32 v91, v86, s95, -v91
	v_fmac_f32_e32 v91, 0x3377d1cf, v86
	v_fmac_f32_e32 v91, 0x3f317217, v86
	s_nop 1
	v_mov_b32_e32 v86, v91
	s_nop 0
	v_log_f32_e32 v87, v87
	s_nop 0
	v_mul_f32_e32 v91, 0x3f317217, v87
	v_fma_f32 v91, v87, s95, -v91
	v_fmac_f32_e32 v91, 0x3377d1cf, v87
	v_fmac_f32_e32 v91, 0x3f317217, v87
	s_nop 1
	v_mov_b32_e32 v87, v91
	v_mul_f32_e32 v91, 0xbfb8aa3b, v92
	v_exp_f32_e32 v91, v91
	s_nop 0
	v_add_f32_e32 v91, 1.0, v91
	v_rcp_f32_e32 v91, v91
	s_nop 0
	v_fma_f32 v80, v91, v114, v80
	v_max_f32_e32 v80, 0xda24260, v80
	s_nop 1
	v_log_f32_e32 v80, v80
	s_nop 0
	v_mul_f32_e32 v91, 0x3f317217, v80
	v_fma_f32 v91, v80, s95, -v91
	v_fmac_f32_e32 v91, 0x3377d1cf, v80
	v_fmac_f32_e32 v91, 0x3f317217, v80
	s_nop 1
	v_mov_b32_e32 v80, v91
	v_mov_b32_e32 v110, v80
	v_fma_f32 v80, v111, v115, v81
	v_max_f32_e32 v80, 0xda24260, v80
	s_nop 1
	v_log_f32_e32 v80, v80
	s_nop 0
	v_mul_f32_e32 v81, 0x3f317217, v80
	v_fma_f32 v81, v80, s95, -v81
	v_fmac_f32_e32 v81, 0x3377d1cf, v80
	v_fmac_f32_e32 v81, 0x3f317217, v80
	s_nop 1
	v_mov_b32_e32 v80, v81
	v_mov_b32_e32 v111, v80
	v_mul_f32_e32 v80, 0xbfb8aa3b, v98
	v_exp_f32_e32 v80, v80
	v_mul_f32_e32 v81, 0xbfb8aa3b, v99
	v_exp_f32_e32 v81, v81
	v_add_f32_e32 v80, 1.0, v80
	v_rcp_f32_e32 v91, v80
	v_add_f32_e32 v81, 1.0, v81
	v_rcp_f32_e32 v113, v81
	v_mul_f32_e32 v80, 0x3fb8aa3b, v98
	v_fma_f32 v82, v91, v116, v82
	v_max_f32_e32 v82, 0xda24260, v82
	v_fmac_f32_e32 v83, v113, v117
	v_mul_f32_e32 v81, 0x3fb8aa3b, v99
	v_log_f32_e32 v82, v82
	v_exp_f32_e32 v80, v80
	v_exp_f32_e32 v81, v81
	v_mul_f32_e32 v91, 0x3f317217, v82
	v_fma_f32 v91, v82, s95, -v91
	v_fmac_f32_e32 v91, 0x3377d1cf, v82
	v_fmac_f32_e32 v91, 0x3f317217, v82
	v_add_f32_e32 v80, 1.0, v80
	v_add_f32_e32 v81, 1.0, v81
	v_mov_b32_e32 v82, v91
	v_mov_b32_e32 v112, v82
	v_max_f32_e32 v82, 0xda24260, v83
	v_rcp_f32_e32 v80, v80
	v_rcp_f32_e32 v81, v81
	v_log_f32_e32 v82, v82
	v_pk_mul_f32 v[80:81], v[80:81], v[116:117]
	v_mul_f32_e32 v83, 0x3f317217, v82
	v_fma_f32 v83, v82, s95, -v83
	v_fmac_f32_e32 v83, 0x3377d1cf, v82
	v_fmac_f32_e32 v83, 0x3f317217, v82
	s_nop 1
	v_mov_b32_e32 v82, v83
	v_mov_b32_e32 v113, v82
	v_pk_mul_f32 v[82:83], v[108:109], v[114:115]
	global_store_dwordx4 v[104:105], v[84:87], off
	global_store_dwordx4 v[104:105], v[110:113], off offset:16

.LBB0_444:
	s_andn2_b64 vcc, exec, s[36:37]
	s_cbranch_vccnz .LBB0_446
	global_load_dwordx4 v[72:75], v[148:149], off offset:528
	global_load_dwordx4 v[76:79], v[148:149], off offset:512
	v_mul_f32_e32 v92, 0xbfb8aa3b, v84
	v_exp_f32_e32 v92, v92
	v_mul_f32_e32 v93, 0xbfb8aa3b, v85
	v_exp_f32_e32 v93, v93
	v_lshl_add_u64 v[88:89], v[150:151], 0, v[88:89]
	v_add_f32_e32 v92, 1.0, v92
	v_rcp_f32_e32 v96, v92
	v_add_f32_e32 v93, 1.0, v93
	v_rcp_f32_e32 v97, v93
	v_mul_f32_e32 v92, 0x3fb8aa3b, v84
	v_mul_f32_e32 v93, 0x3fb8aa3b, v85
	v_exp_f32_e32 v92, v92
	v_exp_f32_e32 v93, v93
	v_add_f32_e32 v92, 1.0, v92
	v_add_f32_e32 v93, 1.0, v93
	v_rcp_f32_e32 v92, v92
	v_rcp_f32_e32 v93, v93
	s_waitcnt vmcnt(1)
	v_pk_add_f32 v[106:107], v[72:73], 1.0 op_sel_hi:[1,0] neg_lo:[1,0] neg_hi:[1,0]
	s_waitcnt vmcnt(0)
	v_pk_add_f32 v[94:95], v[76:77], 1.0 op_sel_hi:[1,0] neg_lo:[1,0] neg_hi:[1,0]
	v_pk_add_f32 v[98:99], v[78:79], 1.0 op_sel_hi:[1,0] neg_lo:[1,0] neg_hi:[1,0]
	v_fma_f32 v76, v96, v94, v76
	v_max_f32_e32 v76, 0xda24260, v76
	v_fma_f32 v77, v97, v95, v77
	v_max_f32_e32 v77, 0xda24260, v77
	v_log_f32_e32 v76, v76
	v_mul_f32_e32 v97, 0xbfb8aa3b, v87
	v_exp_f32_e32 v97, v97
	v_pk_add_f32 v[108:109], v[74:75], 1.0 op_sel_hi:[1,0] neg_lo:[1,0] neg_hi:[1,0]
	v_mul_f32_e32 v96, 0x3f317217, v76
	v_fma_f32 v96, v76, s95, -v96
	v_fmac_f32_e32 v96, 0x3377d1cf, v76
	v_fmac_f32_e32 v96, 0x3f317217, v76
	v_add_f32_e32 v97, 1.0, v97
	v_rcp_f32_e32 v101, v97
	v_mov_b32_e32 v76, v96
	v_fmac_f32_e32 v79, v101, v99
	v_log_f32_e32 v77, v77
	v_max_f32_e32 v79, 0xda24260, v79
	v_mul_f32_e32 v101, 0xbfb8aa3b, v83
	v_exp_f32_e32 v101, v101
	v_mul_f32_e32 v96, 0x3f317217, v77
	v_fma_f32 v96, v77, s95, -v96
	v_fmac_f32_e32 v96, 0x3377d1cf, v77
	v_fmac_f32_e32 v96, 0x3f317217, v77
	v_add_f32_e32 v101, 1.0, v101
	v_rcp_f32_e32 v103, v101
	v_mov_b32_e32 v77, v96
	v_mul_f32_e32 v96, 0xbfb8aa3b, v86
	v_exp_f32_e32 v96, v96
	v_mul_f32_e32 v97, 0x3fb8aa3b, v87
	v_mul_f32_e32 v101, 0x3fb8aa3b, v83
	v_exp_f32_e32 v97, v97
	v_add_f32_e32 v96, 1.0, v96
	v_rcp_f32_e32 v100, v96
	v_mul_f32_e32 v96, 0x3fb8aa3b, v86
	v_exp_f32_e32 v96, v96
	v_exp_f32_e32 v101, v101
	v_fma_f32 v78, v100, v98, v78
	v_max_f32_e32 v78, 0xda24260, v78
	v_add_f32_e32 v96, 1.0, v96
	v_add_f32_e32 v97, 1.0, v97
	v_log_f32_e32 v78, v78
	v_add_f32_e32 v101, 1.0, v101
	v_rcp_f32_e32 v96, v96
	v_rcp_f32_e32 v97, v97
	v_mul_f32_e32 v100, 0x3f317217, v78
	v_fma_f32 v100, v78, s95, -v100
	v_fmac_f32_e32 v100, 0x3377d1cf, v78
	v_fmac_f32_e32 v100, 0x3f317217, v78
	v_rcp_f32_e32 v101, v101
	v_pk_mul_f32 v[94:95], v[92:93], v[94:95]
	v_mov_b32_e32 v78, v100
	v_pk_mul_f32 v[92:93], v[96:97], v[98:99]
	v_log_f32_e32 v79, v79
	s_nop 0
	v_mul_f32_e32 v100, 0x3f317217, v79
	v_fma_f32 v100, v79, s95, -v100
	v_fmac_f32_e32 v100, 0x3377d1cf, v79
	v_fmac_f32_e32 v100, 0x3f317217, v79
	s_nop 1
	v_mov_b32_e32 v79, v100
	v_mul_f32_e32 v100, 0xbfb8aa3b, v82
	v_exp_f32_e32 v100, v100
	s_nop 0
	v_add_f32_e32 v100, 1.0, v100
	v_rcp_f32_e32 v102, v100
	v_mul_f32_e32 v100, 0x3fb8aa3b, v82
	v_exp_f32_e32 v100, v100
	v_fma_f32 v72, v102, v106, v72
	v_max_f32_e32 v72, 0xda24260, v72
	v_add_f32_e32 v100, 1.0, v100
	v_rcp_f32_e32 v100, v100
	v_log_f32_e32 v72, v72
	s_nop 0
	v_mul_f32_e32 v102, 0x3f317217, v72
	v_fma_f32 v102, v72, s95, -v102
	v_fmac_f32_e32 v102, 0x3377d1cf, v72
	v_fmac_f32_e32 v102, 0x3f317217, v72
	s_nop 1
	v_mov_b32_e32 v72, v102
	v_mov_b32_e32 v102, v72
	v_fma_f32 v72, v103, v107, v73
	v_max_f32_e32 v72, 0xda24260, v72
	s_nop 1
	v_log_f32_e32 v72, v72
	s_nop 0
	v_mul_f32_e32 v73, 0x3f317217, v72
	v_fma_f32 v73, v72, s95, -v73
	v_fmac_f32_e32 v73, 0x3377d1cf, v72
	v_fmac_f32_e32 v73, 0x3f317217, v72
	s_nop 1
	v_mov_b32_e32 v72, v73
	v_mov_b32_e32 v103, v72
	v_mul_f32_e32 v72, 0xbfb8aa3b, v90
	v_exp_f32_e32 v72, v72
	v_mul_f32_e32 v73, 0xbfb8aa3b, v91
	v_exp_f32_e32 v73, v73
	v_add_f32_e32 v72, 1.0, v72
	v_rcp_f32_e32 v104, v72
	v_add_f32_e32 v73, 1.0, v73
	v_rcp_f32_e32 v105, v73
	v_mul_f32_e32 v72, 0x3fb8aa3b, v90
	v_fma_f32 v74, v104, v108, v74
	v_max_f32_e32 v74, 0xda24260, v74
	v_fmac_f32_e32 v75, v105, v109
	v_mul_f32_e32 v73, 0x3fb8aa3b, v91
	v_log_f32_e32 v74, v74
	v_exp_f32_e32 v72, v72
	v_exp_f32_e32 v73, v73
	v_mul_f32_e32 v104, 0x3f317217, v74
	v_fma_f32 v104, v74, s95, -v104
	v_fmac_f32_e32 v104, 0x3377d1cf, v74
	v_fmac_f32_e32 v104, 0x3f317217, v74
	v_add_f32_e32 v72, 1.0, v72
	v_add_f32_e32 v73, 1.0, v73
	v_mov_b32_e32 v74, v104
	v_mov_b32_e32 v104, v74
	v_max_f32_e32 v74, 0xda24260, v75
	v_rcp_f32_e32 v72, v72
	v_rcp_f32_e32 v73, v73
	v_log_f32_e32 v74, v74
	v_pk_mul_f32 v[72:73], v[72:73], v[108:109]
	v_mul_f32_e32 v75, 0x3f317217, v74
	v_fma_f32 v75, v74, s95, -v75
	v_fmac_f32_e32 v75, 0x3377d1cf, v74
	v_fmac_f32_e32 v75, 0x3f317217, v74
	s_nop 1
	v_mov_b32_e32 v74, v75
	v_mov_b32_e32 v105, v74
	v_pk_mul_f32 v[74:75], v[100:101], v[106:107]
	global_store_dwordx4 v[88:89], v[76:79], off
	global_store_dwordx4 v[88:89], v[102:105], off offset:16

.LBB0_456:
	s_andn2_b64 vcc, exec, s[36:37]
	s_cbranch_vccnz .LBB0_458
	v_mul_f32_e32 v72, 0xbfb8aa3b, v86
	v_exp_f32_e32 v72, v72
	v_mul_f32_e32 v97, 0xbfb8aa3b, v89
	v_exp_f32_e32 v97, v97
	v_mul_f32_e32 v101, 0xbfb8aa3b, v85
	v_add_f32_e32 v72, 1.0, v72
	v_rcp_f32_e32 v83, v72
	v_mul_f32_e32 v72, 0x3fb8aa3b, v86
	v_exp_f32_e32 v72, v72
	v_add_f32_e32 v97, 1.0, v97
	v_rcp_f32_e32 v100, v97
	v_exp_f32_e32 v101, v101
	v_add_f32_e32 v72, 1.0, v72
	v_rcp_f32_e32 v92, v72
	v_mul_f32_e32 v72, 0xbfb8aa3b, v87
	v_exp_f32_e32 v72, v72
	v_add_f32_e32 v101, 1.0, v101
	v_rcp_f32_e32 v103, v101
	v_mul_f32_e32 v97, 0x3fb8aa3b, v89
	v_add_f32_e32 v72, 1.0, v72
	v_rcp_f32_e32 v96, v72
	v_mul_f32_e32 v72, 0x3fb8aa3b, v87
	v_exp_f32_e32 v72, v72
	v_mul_f32_e32 v101, 0x3fb8aa3b, v85
	v_exp_f32_e32 v97, v97
	v_exp_f32_e32 v101, v101
	v_add_f32_e32 v72, 1.0, v72
	v_rcp_f32_e32 v93, v72
	global_load_dwordx4 v[72:75], v[148:149], off offset:16
	global_load_dwordx4 v[76:79], v[148:149], off
	v_add_f32_e32 v97, 1.0, v97
	v_add_f32_e32 v101, 1.0, v101
	v_rcp_f32_e32 v97, v97
	v_rcp_f32_e32 v101, v101
	s_waitcnt vmcnt(1)
	v_pk_add_f32 v[106:107], v[72:73], 1.0 op_sel_hi:[1,0] neg_lo:[1,0] neg_hi:[1,0]
	s_waitcnt vmcnt(0)
	v_pk_add_f32 v[94:95], v[76:77], 1.0 op_sel_hi:[1,0] neg_lo:[1,0] neg_hi:[1,0]
	v_pk_add_f32 v[98:99], v[78:79], 1.0 op_sel_hi:[1,0] neg_lo:[1,0] neg_hi:[1,0]
	v_fma_f32 v76, v83, v94, v76
	v_max_f32_e32 v76, 0xda24260, v76
	v_fma_f32 v77, v96, v95, v77
	v_max_f32_e32 v77, 0xda24260, v77
	v_log_f32_e32 v76, v76
	v_fmac_f32_e32 v79, v100, v99
	v_max_f32_e32 v79, 0xda24260, v79
	v_pk_add_f32 v[108:109], v[74:75], 1.0 op_sel_hi:[1,0] neg_lo:[1,0] neg_hi:[1,0]
	v_mul_f32_e32 v83, 0x3f317217, v76
	v_fma_f32 v83, v76, s95, -v83
	v_fmac_f32_e32 v83, 0x3377d1cf, v76
	v_fmac_f32_e32 v83, 0x3f317217, v76
	v_mul_f32_e32 v96, 0x3fb8aa3b, v88
	v_mul_f32_e32 v100, 0x3fb8aa3b, v84
	v_mov_b32_e32 v76, v83
	v_exp_f32_e32 v96, v96
	v_log_f32_e32 v77, v77
	v_exp_f32_e32 v100, v100
	v_add_f32_e32 v96, 1.0, v96
	v_rcp_f32_e32 v96, v96
	v_mul_f32_e32 v83, 0x3f317217, v77
	v_fma_f32 v83, v77, s95, -v83
	v_fmac_f32_e32 v83, 0x3377d1cf, v77
	v_fmac_f32_e32 v83, 0x3f317217, v77
	v_add_f32_e32 v100, 1.0, v100
	v_rcp_f32_e32 v100, v100
	v_mov_b32_e32 v77, v83
	v_mul_f32_e32 v83, 0xbfb8aa3b, v88
	v_exp_f32_e32 v83, v83
	v_pk_mul_f32 v[94:95], v[92:93], v[94:95]
	v_pk_mul_f32 v[92:93], v[96:97], v[98:99]
	v_lshl_add_u64 v[96:97], v[146:147], 0, v[80:81]
	v_add_f32_e32 v83, 1.0, v83
	v_rcp_f32_e32 v83, v83
	s_nop 0
	v_fma_f32 v78, v83, v98, v78
	v_max_f32_e32 v78, 0xda24260, v78
	s_nop 1
	v_log_f32_e32 v78, v78
	s_nop 0
	v_mul_f32_e32 v83, 0x3f317217, v78
	v_fma_f32 v83, v78, s95, -v83
	v_fmac_f32_e32 v83, 0x3377d1cf, v78
	v_fmac_f32_e32 v83, 0x3f317217, v78
	s_nop 1
	v_mov_b32_e32 v78, v83
	s_nop 0
	v_log_f32_e32 v79, v79
	s_nop 0
	v_mul_f32_e32 v83, 0x3f317217, v79
	v_fma_f32 v83, v79, s95, -v83
	v_fmac_f32_e32 v83, 0x3377d1cf, v79
	v_fmac_f32_e32 v83, 0x3f317217, v79
	s_nop 1
	v_mov_b32_e32 v79, v83
	v_mul_f32_e32 v83, 0xbfb8aa3b, v84
	v_exp_f32_e32 v83, v83
	s_nop 0
	v_add_f32_e32 v83, 1.0, v83
	v_rcp_f32_e32 v83, v83
	s_nop 0
	v_fma_f32 v72, v83, v106, v72
	v_max_f32_e32 v72, 0xda24260, v72
	s_nop 1
	v_log_f32_e32 v72, v72
	s_nop 0
	v_mul_f32_e32 v83, 0x3f317217, v72
	v_fma_f32 v83, v72, s95, -v83
	v_fmac_f32_e32 v83, 0x3377d1cf, v72
	v_fmac_f32_e32 v83, 0x3f317217, v72
	s_nop 1
	v_mov_b32_e32 v72, v83
	v_mov_b32_e32 v102, v72
	v_fma_f32 v72, v103, v107, v73
	v_max_f32_e32 v72, 0xda24260, v72
	s_nop 1
	v_log_f32_e32 v72, v72
	s_nop 0
	v_mul_f32_e32 v73, 0x3f317217, v72
	v_fma_f32 v73, v72, s95, -v73
	v_fmac_f32_e32 v73, 0x3377d1cf, v72
	v_fmac_f32_e32 v73, 0x3f317217, v72
	s_nop 1
	v_mov_b32_e32 v72, v73
	v_mov_b32_e32 v103, v72
	v_mul_f32_e32 v72, 0xbfb8aa3b, v90
	v_exp_f32_e32 v72, v72
	v_mul_f32_e32 v73, 0xbfb8aa3b, v91
	v_exp_f32_e32 v73, v73
	v_add_f32_e32 v72, 1.0, v72
	v_rcp_f32_e32 v83, v72
	v_add_f32_e32 v73, 1.0, v73
	v_rcp_f32_e32 v105, v73
	v_mul_f32_e32 v72, 0x3fb8aa3b, v90
	v_fma_f32 v74, v83, v108, v74
	v_max_f32_e32 v74, 0xda24260, v74
	v_fmac_f32_e32 v75, v105, v109
	v_mul_f32_e32 v73, 0x3fb8aa3b, v91
	v_log_f32_e32 v74, v74
	v_exp_f32_e32 v72, v72
	v_exp_f32_e32 v73, v73
	v_mul_f32_e32 v83, 0x3f317217, v74
	v_fma_f32 v83, v74, s95, -v83
	v_fmac_f32_e32 v83, 0x3377d1cf, v74
	v_fmac_f32_e32 v83, 0x3f317217, v74
	v_add_f32_e32 v72, 1.0, v72
	v_add_f32_e32 v73, 1.0, v73
	v_mov_b32_e32 v74, v83
	v_mov_b32_e32 v104, v74
	v_max_f32_e32 v74, 0xda24260, v75
	v_rcp_f32_e32 v72, v72
	v_rcp_f32_e32 v73, v73
	v_log_f32_e32 v74, v74
	v_pk_mul_f32 v[72:73], v[72:73], v[108:109]
	v_mul_f32_e32 v75, 0x3f317217, v74
	v_fma_f32 v75, v74, s95, -v75
	v_fmac_f32_e32 v75, 0x3377d1cf, v74
	v_fmac_f32_e32 v75, 0x3f317217, v74
	s_nop 1
	v_mov_b32_e32 v74, v75
	v_mov_b32_e32 v105, v74
	v_pk_mul_f32 v[74:75], v[100:101], v[106:107]
	global_store_dwordx4 v[96:97], v[76:79], off
	global_store_dwordx4 v[96:97], v[102:105], off offset:16

.LBB0_468:
	s_andn2_b64 vcc, exec, s[30:31]
	s_cbranch_vccnz .LBB0_470
	global_load_dwordx4 v[64:67], v[148:149], off offset:528
	global_load_dwordx4 v[68:71], v[148:149], off offset:512
	v_mul_f32_e32 v84, 0xbfb8aa3b, v76
	v_exp_f32_e32 v84, v84
	v_mul_f32_e32 v85, 0xbfb8aa3b, v77
	v_exp_f32_e32 v85, v85
	v_lshl_add_u64 v[80:81], v[150:151], 0, v[80:81]
	v_add_f32_e32 v84, 1.0, v84
	v_rcp_f32_e32 v88, v84
	v_add_f32_e32 v85, 1.0, v85
	v_rcp_f32_e32 v89, v85
	v_mul_f32_e32 v84, 0x3fb8aa3b, v76
	v_mul_f32_e32 v85, 0x3fb8aa3b, v77
	v_exp_f32_e32 v84, v84
	v_exp_f32_e32 v85, v85
	v_add_f32_e32 v84, 1.0, v84
	v_add_f32_e32 v85, 1.0, v85
	v_rcp_f32_e32 v84, v84
	v_rcp_f32_e32 v85, v85
	s_waitcnt vmcnt(1)
	v_pk_add_f32 v[98:99], v[64:65], 1.0 op_sel_hi:[1,0] neg_lo:[1,0] neg_hi:[1,0]
	s_waitcnt vmcnt(0)
	v_pk_add_f32 v[86:87], v[68:69], 1.0 op_sel_hi:[1,0] neg_lo:[1,0] neg_hi:[1,0]
	v_pk_add_f32 v[90:91], v[70:71], 1.0 op_sel_hi:[1,0] neg_lo:[1,0] neg_hi:[1,0]
	v_fma_f32 v68, v88, v86, v68
	v_max_f32_e32 v68, 0xda24260, v68
	v_fma_f32 v69, v89, v87, v69
	v_max_f32_e32 v69, 0xda24260, v69
	v_log_f32_e32 v68, v68
	v_mul_f32_e32 v89, 0xbfb8aa3b, v79
	v_exp_f32_e32 v89, v89
	v_pk_add_f32 v[100:101], v[66:67], 1.0 op_sel_hi:[1,0] neg_lo:[1,0] neg_hi:[1,0]
	v_mul_f32_e32 v88, 0x3f317217, v68
	v_fma_f32 v88, v68, s95, -v88
	v_fmac_f32_e32 v88, 0x3377d1cf, v68
	v_fmac_f32_e32 v88, 0x3f317217, v68
	v_add_f32_e32 v89, 1.0, v89
	v_rcp_f32_e32 v93, v89
	v_mov_b32_e32 v68, v88
	v_fmac_f32_e32 v71, v93, v91
	v_log_f32_e32 v69, v69
	v_max_f32_e32 v71, 0xda24260, v71
	v_mul_f32_e32 v93, 0xbfb8aa3b, v75
	v_exp_f32_e32 v93, v93
	v_mul_f32_e32 v88, 0x3f317217, v69
	v_fma_f32 v88, v69, s95, -v88
	v_fmac_f32_e32 v88, 0x3377d1cf, v69
	v_fmac_f32_e32 v88, 0x3f317217, v69
	v_add_f32_e32 v93, 1.0, v93
	v_rcp_f32_e32 v95, v93
	v_mov_b32_e32 v69, v88
	v_mul_f32_e32 v88, 0xbfb8aa3b, v78
	v_exp_f32_e32 v88, v88
	v_mul_f32_e32 v89, 0x3fb8aa3b, v79
	v_mul_f32_e32 v93, 0x3fb8aa3b, v75
	v_exp_f32_e32 v89, v89
	v_add_f32_e32 v88, 1.0, v88
	v_rcp_f32_e32 v92, v88
	v_mul_f32_e32 v88, 0x3fb8aa3b, v78
	v_exp_f32_e32 v88, v88
	v_exp_f32_e32 v93, v93
	v_fma_f32 v70, v92, v90, v70
	v_max_f32_e32 v70, 0xda24260, v70
	v_add_f32_e32 v88, 1.0, v88
	v_add_f32_e32 v89, 1.0, v89
	v_log_f32_e32 v70, v70
	v_add_f32_e32 v93, 1.0, v93
	v_rcp_f32_e32 v88, v88
	v_rcp_f32_e32 v89, v89
	v_mul_f32_e32 v92, 0x3f317217, v70
	v_fma_f32 v92, v70, s95, -v92
	v_fmac_f32_e32 v92, 0x3377d1cf, v70
	v_fmac_f32_e32 v92, 0x3f317217, v70
	v_rcp_f32_e32 v93, v93
	v_pk_mul_f32 v[86:87], v[84:85], v[86:87]
	v_mov_b32_e32 v70, v92
	v_pk_mul_f32 v[84:85], v[88:89], v[90:91]
	v_log_f32_e32 v71, v71
	s_nop 0
	v_mul_f32_e32 v92, 0x3f317217, v71
	v_fma_f32 v92, v71, s95, -v92
	v_fmac_f32_e32 v92, 0x3377d1cf, v71
	v_fmac_f32_e32 v92, 0x3f317217, v71
	s_nop 1
	v_mov_b32_e32 v71, v92
	v_mul_f32_e32 v92, 0xbfb8aa3b, v74
	v_exp_f32_e32 v92, v92
	s_nop 0
	v_add_f32_e32 v92, 1.0, v92
	v_rcp_f32_e32 v94, v92
	v_mul_f32_e32 v92, 0x3fb8aa3b, v74
	v_exp_f32_e32 v92, v92
	v_fma_f32 v64, v94, v98, v64
	v_max_f32_e32 v64, 0xda24260, v64
	v_add_f32_e32 v92, 1.0, v92
	v_rcp_f32_e32 v92, v92
	v_log_f32_e32 v64, v64
	s_nop 0
	v_mul_f32_e32 v94, 0x3f317217, v64
	v_fma_f32 v94, v64, s95, -v94
	v_fmac_f32_e32 v94, 0x3377d1cf, v64
	v_fmac_f32_e32 v94, 0x3f317217, v64
	s_nop 1
	v_mov_b32_e32 v64, v94
	v_mov_b32_e32 v94, v64
	v_fma_f32 v64, v95, v99, v65
	v_max_f32_e32 v64, 0xda24260, v64
	s_nop 1
	v_log_f32_e32 v64, v64
	s_nop 0
	v_mul_f32_e32 v65, 0x3f317217, v64
	v_fma_f32 v65, v64, s95, -v65
	v_fmac_f32_e32 v65, 0x3377d1cf, v64
	v_fmac_f32_e32 v65, 0x3f317217, v64
	s_nop 1
	v_mov_b32_e32 v64, v65
	v_mov_b32_e32 v95, v64
	v_mul_f32_e32 v64, 0xbfb8aa3b, v82
	v_exp_f32_e32 v64, v64
	v_mul_f32_e32 v65, 0xbfb8aa3b, v83
	v_exp_f32_e32 v65, v65
	v_add_f32_e32 v64, 1.0, v64
	v_rcp_f32_e32 v96, v64
	v_add_f32_e32 v65, 1.0, v65
	v_rcp_f32_e32 v97, v65
	v_mul_f32_e32 v64, 0x3fb8aa3b, v82
	v_fma_f32 v66, v96, v100, v66
	v_max_f32_e32 v66, 0xda24260, v66
	v_fmac_f32_e32 v67, v97, v101
	v_mul_f32_e32 v65, 0x3fb8aa3b, v83
	v_log_f32_e32 v66, v66
	v_exp_f32_e32 v64, v64
	v_exp_f32_e32 v65, v65
	v_mul_f32_e32 v96, 0x3f317217, v66
	v_fma_f32 v96, v66, s95, -v96
	v_fmac_f32_e32 v96, 0x3377d1cf, v66
	v_fmac_f32_e32 v96, 0x3f317217, v66
	v_add_f32_e32 v64, 1.0, v64
	v_add_f32_e32 v65, 1.0, v65
	v_mov_b32_e32 v66, v96
	v_mov_b32_e32 v96, v66
	v_max_f32_e32 v66, 0xda24260, v67
	v_rcp_f32_e32 v64, v64
	v_rcp_f32_e32 v65, v65
	v_log_f32_e32 v66, v66
	v_pk_mul_f32 v[64:65], v[64:65], v[100:101]
	v_mul_f32_e32 v67, 0x3f317217, v66
	v_fma_f32 v67, v66, s95, -v67
	v_fmac_f32_e32 v67, 0x3377d1cf, v66
	v_fmac_f32_e32 v67, 0x3f317217, v66
	s_nop 1
	v_mov_b32_e32 v66, v67
	v_mov_b32_e32 v97, v66
	v_pk_mul_f32 v[66:67], v[92:93], v[98:99]
	global_store_dwordx4 v[80:81], v[68:71], off
	global_store_dwordx4 v[80:81], v[94:97], off offset:16
